# GEMM K-loop LDS-DMA uses SGPR-base + 32-bit VGPR offset (saddr) form, removing 16 v_lshl_add_u64 per iteration (on top of the f32 store regrouping)
# speedup vs baseline: 1.0146x; 1.0022x over previous
; #define PG8_STAGE(bufoff, gbase, voff) do { _Pragma("unroll") for (int _i = 0; _i < 2; ++_i) \
;         __builtin_amdgcn_global_load_lds((const unsigned*)((const char*)(gbase) + (voff)[_i]), (PG8_LAS unsigned*)(lds + (bufoff) + ldsw + _i * 8192), 16, 0, 0); } while (0)
; #define PG8_LDA(dst, b, h) do { _Pragma("unroll") for (int m = 0; m < 4; ++m) _Pragma("unroll") for (int k = 0; k < 2; ++k) dst[m][k] = *(const PG8_LAS bf16x8*)(lds + PG8_SA(b, h) + aoff + m * 2048 + k * 1024); } while (0)
; #define PG8_LDB(dst, b, h) do { _Pragma("unroll") for (int n = 0; n < 2; ++n) _Pragma("unroll") for (int k = 0; k < 2; ++k) dst[n][k] = *(const PG8_LAS bf16x8*)(lds + PG8_SB(b, h) + boff + n * 2048 + k * 1024); } while (0)
; #define PG8_MMA(ai, bj, At, Bt) do { __builtin_amdgcn_s_setprio(1); _Pragma("unroll") for (int m = 0; m < 4; ++m) _Pragma("unroll") for (int n = 0; n < 2; ++n) _Pragma("unroll") for (int k = 0; k < 2; ++k) \
;         acc[ai][bj][m][n] = __builtin_amdgcn_mfma_f32_16x16x32_bf16(Bt[n][k], At[m][k], acc[ai][bj][m][n], 0, 0, 0); __builtin_amdgcn_s_setprio(0); } while (0)
; #define PG8_WAIT_V(n) asm volatile("s_waitcnt vmcnt(" #n ")" ::: "memory")
; #define PG8_WAIT_L(n) asm volatile("s_waitcnt lgkmcnt(" #n ")" ::: "memory")
; #define PG8_BAR __builtin_amdgcn_s_barrier()
; template <class Epi, class Sched, bool ALIGN_EPI = false, bool SP2 = false>
; __device__ __forceinline__ void gemm_phase(PG8_LAS unsigned char* lds, const Gemm g, const Sched& S, const Epi& E) {
;     ...
;             const char* a1 = cA + (size_t)(t + 1) * kstep;
;             const char* a2 = last ? nA : cA + (size_t)(t + 2) * kstep; const char* b2 = last ? nB : cB + (size_t)(t + 2) * kstep;
;             const char* a3 = a2 + kstep; const char* b3 = b2 + kstep;
;             if (last && has_next) S.a_ready(nxt);
;             if constexpr (SP2) {
;             PG8_LDB(B0, 0, 0); PG8_LDB(B1, 0, 1); PG8_SCHED; PG8_LDA(At, 0, 0); PG8_STAGE(PG8_SA(1, 1), a1 + hstep, voffA);
;             PG8_WAIT_V(8); PG8_WAIT_L(0); PG8_BAR; PG8_MMA(0, 0, At, B0); PG8_MMA(0, 1, At, B1); PG8_BAR; PG8_SCHED;
;             PG8_LDA(At, 0, 1); PG8_STAGE(PG8_SB(0, 0), b2, voffB); PG8_STAGE(PG8_SB(0, 1), b2 + hstep, voffB); PG8_STAGE(PG8_SA(0, 0), a2, voffA);
;             PG8_WAIT_V(8); PG8_WAIT_L(0); PG8_BAR; PG8_MMA(1, 0, At, B0); PG8_MMA(1, 1, At, B1); PG8_BAR; PG8_SCHED;
.LBB0_130:
	s_nop 0
	ds_read_b128 v[128:131], v171
	ds_read_b128 v[132:135], v171 offset:1024
	ds_read_b128 v[136:139], v171 offset:2048
	ds_read_b128 v[140:143], v171 offset:3072
	ds_read_b128 v[160:163], v172
	ds_read_b128 v[176:179], v172 offset:1024
	ds_read_b128 v[180:183], v172 offset:2048
	ds_read_b128 v[184:187], v172 offset:3072
	s_add_u32 s28, s26, 0xfffc0080
	s_addc_u32 s29, s27, -1
	s_cmp_eq_u32 s54, 12
	s_cselect_b32 s31, s17, s29
	s_cselect_b32 s30, s50, s28
	s_cselect_b32 s29, s15, s53
	s_cselect_b32 s28, s51, s52
	s_add_i32 m0, s25, 0xc000
	ds_read_b128 v[188:191], v173
	ds_read_b128 v[192:195], v173 offset:1024
	ds_read_b128 v[196:199], v173 offset:2048
	ds_read_b128 v[200:203], v173 offset:3072
	ds_read_b128 v[204:207], v173 offset:4096
	ds_read_b128 v[208:211], v173 offset:5120
	ds_read_b128 v[212:215], v173 offset:6144
	ds_read_b128 v[216:219], v173 offset:7168
	global_load_lds_dwordx4 v152, s[26:27]
	s_add_i32 m0, s25, 0xe000
	s_nop 0
	global_load_lds_dwordx4 v154, s[26:27]
	s_waitcnt vmcnt(8)
	s_waitcnt lgkmcnt(0)
	s_barrier
	s_setprio 1
	s_waitcnt lgkmcnt(0)
	v_mfma_f32_16x16x32_bf16 v[124:127], v[128:131], v[188:191], v[124:127]
	v_mfma_f32_16x16x32_bf16 v[120:123], v[136:139], v[188:191], v[120:123]
	v_mfma_f32_16x16x32_bf16 v[116:119], v[128:131], v[196:199], v[116:119]
	v_mfma_f32_16x16x32_bf16 v[108:111], v[136:139], v[196:199], v[108:111]
	v_mfma_f32_16x16x32_bf16 v[96:99], v[128:131], v[204:207], v[96:99]
	v_mfma_f32_16x16x32_bf16 v[88:91], v[136:139], v[204:207], v[88:91]
	v_mfma_f32_16x16x32_bf16 v[84:87], v[128:131], v[212:215], v[84:87]
	v_mfma_f32_16x16x32_bf16 v[76:79], v[136:139], v[212:215], v[76:79]
	v_mfma_f32_16x16x32_bf16 v[124:127], v[132:135], v[192:195], v[124:127]
	v_mfma_f32_16x16x32_bf16 v[120:123], v[140:143], v[192:195], v[120:123]
	v_mfma_f32_16x16x32_bf16 v[116:119], v[132:135], v[200:203], v[116:119]
	v_mfma_f32_16x16x32_bf16 v[108:111], v[140:143], v[200:203], v[108:111]
	v_mfma_f32_16x16x32_bf16 v[96:99], v[132:135], v[208:211], v[96:99]
	v_mfma_f32_16x16x32_bf16 v[88:91], v[140:143], v[208:211], v[88:91]
	v_mfma_f32_16x16x32_bf16 v[84:87], v[132:135], v[216:219], v[84:87]
	v_mfma_f32_16x16x32_bf16 v[76:79], v[140:143], v[216:219], v[76:79]
	s_setprio 0
	s_setprio 1
	v_mfma_f32_16x16x32_bf16 v[112:115], v[160:163], v[188:191], v[112:115]
	v_mfma_f32_16x16x32_bf16 v[104:107], v[180:183], v[188:191], v[104:107]
	v_mfma_f32_16x16x32_bf16 v[100:103], v[160:163], v[196:199], v[100:103]
	v_mfma_f32_16x16x32_bf16 v[92:95], v[180:183], v[196:199], v[92:95]
	v_mfma_f32_16x16x32_bf16 v[80:83], v[160:163], v[204:207], v[80:83]
	v_mfma_f32_16x16x32_bf16 v[72:75], v[180:183], v[204:207], v[72:75]
	v_mfma_f32_16x16x32_bf16 v[68:71], v[160:163], v[212:215], v[68:71]
	v_mfma_f32_16x16x32_bf16 v[64:67], v[180:183], v[212:215], v[64:67]
	v_mfma_f32_16x16x32_bf16 v[112:115], v[176:179], v[192:195], v[112:115]
	v_mfma_f32_16x16x32_bf16 v[104:107], v[184:187], v[192:195], v[104:107]
	v_mfma_f32_16x16x32_bf16 v[100:103], v[176:179], v[200:203], v[100:103]
	v_mfma_f32_16x16x32_bf16 v[92:95], v[184:187], v[200:203], v[92:95]
	v_mfma_f32_16x16x32_bf16 v[80:83], v[176:179], v[208:211], v[80:83]
	v_mfma_f32_16x16x32_bf16 v[72:75], v[184:187], v[208:211], v[72:75]
	v_mfma_f32_16x16x32_bf16 v[68:71], v[176:179], v[216:219], v[68:71]
	v_mfma_f32_16x16x32_bf16 v[64:67], v[184:187], v[216:219], v[64:67]
	s_setprio 0
	s_barrier
	s_add_i32 s55, s44, s22
	s_mov_b32 m0, s55
	ds_read_b128 v[188:191], v173 offset:16384
	ds_read_b128 v[192:195], v173 offset:17408
	ds_read_b128 v[196:199], v173 offset:18432
	ds_read_b128 v[200:203], v173 offset:19456
	ds_read_b128 v[204:207], v173 offset:20480
	ds_read_b128 v[208:211], v173 offset:21504
	ds_read_b128 v[212:215], v173 offset:22528
	ds_read_b128 v[216:219], v173 offset:23552
	global_load_lds_dwordx4 v146, s[28:29]
	s_add_i32 m0, s55, 0x2000
	s_add_u32 s56, s28, 0x40000
	s_addc_u32 s57, s29, 0
	s_add_i32 s55, s45, s22
	global_load_lds_dwordx4 v150, s[28:29]
	s_mov_b32 m0, s55
	s_nop 0
	global_load_lds_dwordx4 v146, s[56:57]
	s_add_i32 m0, s55, 0x2000
	s_nop 0
	global_load_lds_dwordx4 v150, s[56:57]
	s_mov_b32 m0, s25
	s_nop 0
	global_load_lds_dwordx4 v144, s[30:31]
	s_mov_b32 m0, s36
	s_nop 0
	global_load_lds_dwordx4 v148, s[30:31]
	s_waitcnt vmcnt(8)
	s_waitcnt lgkmcnt(0)
	s_barrier
	s_setprio 1
	s_waitcnt lgkmcnt(0)
	v_mfma_f32_16x16x32_bf16 v[60:63], v[128:131], v[188:191], v[60:63]
	v_mfma_f32_16x16x32_bf16 v[56:59], v[136:139], v[188:191], v[56:59]
	v_mfma_f32_16x16x32_bf16 v[52:55], v[128:131], v[196:199], v[52:55]
	v_mfma_f32_16x16x32_bf16 v[44:47], v[136:139], v[196:199], v[44:47]
	v_mfma_f32_16x16x32_bf16 v[32:35], v[128:131], v[204:207], v[32:35]
	v_mfma_f32_16x16x32_bf16 v[24:27], v[136:139], v[204:207], v[24:27]
	v_mfma_f32_16x16x32_bf16 v[20:23], v[128:131], v[212:215], v[20:23]
	v_mfma_f32_16x16x32_bf16 v[12:15], v[136:139], v[212:215], v[12:15]
	v_mfma_f32_16x16x32_bf16 v[60:63], v[132:135], v[192:195], v[60:63]
	v_mfma_f32_16x16x32_bf16 v[56:59], v[140:143], v[192:195], v[56:59]
	v_mfma_f32_16x16x32_bf16 v[52:55], v[132:135], v[200:203], v[52:55]
	v_mfma_f32_16x16x32_bf16 v[44:47], v[140:143], v[200:203], v[44:47]
	v_mfma_f32_16x16x32_bf16 v[32:35], v[132:135], v[208:211], v[32:35]
	v_mfma_f32_16x16x32_bf16 v[24:27], v[140:143], v[208:211], v[24:27]
	v_mfma_f32_16x16x32_bf16 v[20:23], v[132:135], v[216:219], v[20:23]
	v_mfma_f32_16x16x32_bf16 v[12:15], v[140:143], v[216:219], v[12:15]
	s_setprio 0
	s_setprio 1
	v_mfma_f32_16x16x32_bf16 v[48:51], v[160:163], v[188:191], v[48:51]
	v_mfma_f32_16x16x32_bf16 v[40:43], v[180:183], v[188:191], v[40:43]
	v_mfma_f32_16x16x32_bf16 v[36:39], v[160:163], v[196:199], v[36:39]
	v_mfma_f32_16x16x32_bf16 v[28:31], v[180:183], v[196:199], v[28:31]
	v_mfma_f32_16x16x32_bf16 v[16:19], v[160:163], v[204:207], v[16:19]
	v_mfma_f32_16x16x32_bf16 v[8:11], v[180:183], v[204:207], v[8:11]
	v_mfma_f32_16x16x32_bf16 v[4:7], v[160:163], v[212:215], v[4:7]
	v_mfma_f32_16x16x32_bf16 v[0:3], v[180:183], v[212:215], v[0:3]
	v_mfma_f32_16x16x32_bf16 v[48:51], v[176:179], v[192:195], v[48:51]
	v_mfma_f32_16x16x32_bf16 v[40:43], v[184:187], v[192:195], v[40:43]
	v_mfma_f32_16x16x32_bf16 v[36:39], v[176:179], v[200:203], v[36:39]
	v_mfma_f32_16x16x32_bf16 v[28:31], v[184:187], v[200:203], v[28:31]
	v_mfma_f32_16x16x32_bf16 v[16:19], v[176:179], v[208:211], v[16:19]
	v_mfma_f32_16x16x32_bf16 v[8:11], v[184:187], v[208:211], v[8:11]
	v_mfma_f32_16x16x32_bf16 v[4:7], v[176:179], v[216:219], v[4:7]
	v_mfma_f32_16x16x32_bf16 v[0:3], v[184:187], v[216:219], v[0:3]
	s_setprio 0
	s_barrier
; #define PG8_STAGE(bufoff, gbase, voff) do { _Pragma("unroll") for (int _i = 0; _i < 2; ++_i) \
;         __builtin_amdgcn_global_load_lds((const unsigned*)((const char*)(gbase) + (voff)[_i]), (PG8_LAS unsigned*)(lds + (bufoff) + ldsw + _i * 8192), 16, 0, 0); } while (0)
; #define PG8_LDA(dst, b, h) do { _Pragma("unroll") for (int m = 0; m < 4; ++m) _Pragma("unroll") for (int k = 0; k < 2; ++k) dst[m][k] = *(const PG8_LAS bf16x8*)(lds + PG8_SA(b, h) + aoff + m * 2048 + k * 1024); } while (0)
; #define PG8_LDB(dst, b, h) do { _Pragma("unroll") for (int n = 0; n < 2; ++n) _Pragma("unroll") for (int k = 0; k < 2; ++k) dst[n][k] = *(const PG8_LAS bf16x8*)(lds + PG8_SB(b, h) + boff + n * 2048 + k * 1024); } while (0)
; #define PG8_MMA(ai, bj, At, Bt) do { __builtin_amdgcn_s_setprio(1); _Pragma("unroll") for (int m = 0; m < 4; ++m) _Pragma("unroll") for (int n = 0; n < 2; ++n) _Pragma("unroll") for (int k = 0; k < 2; ++k) \
;         acc[ai][bj][m][n] = __builtin_amdgcn_mfma_f32_16x16x32_bf16(Bt[n][k], At[m][k], acc[ai][bj][m][n], 0, 0, 0); __builtin_amdgcn_s_setprio(0); } while (0)
; #define PG8_WAIT_V(n) asm volatile("s_waitcnt vmcnt(" #n ")" ::: "memory")
; #define PG8_WAIT_L(n) asm volatile("s_waitcnt lgkmcnt(" #n ")" ::: "memory")
; #define PG8_BAR __builtin_amdgcn_s_barrier()
; #define PG8_SCHED __builtin_amdgcn_sched_barrier(0)
; template <class Epi, class Sched, bool ALIGN_EPI = false, bool SP2 = false>
; __device__ __forceinline__ void gemm_phase(PG8_LAS unsigned char* lds, const Gemm g, const Sched& S, const Epi& E) {
;     ...
;             PG8_LDB(B0, 1, 0); PG8_LDB(B1, 1, 1); PG8_SCHED; PG8_LDA(At, 1, 0); PG8_STAGE(PG8_SA(0, 1), a2 + hstep, voffA);
;             PG8_WAIT_V(8); PG8_WAIT_L(0); PG8_BAR; PG8_MMA(0, 0, At, B0); PG8_MMA(0, 1, At, B1); PG8_BAR; PG8_SCHED;
;             PG8_LDA(At, 1, 1); PG8_STAGE(PG8_SB(1, 0), b3, voffB); PG8_STAGE(PG8_SB(1, 1), b3 + hstep, voffB); PG8_STAGE(PG8_SA(1, 0), a3, voffA);
;             PG8_WAIT_V(8); PG8_WAIT_L(0); PG8_BAR; PG8_MMA(1, 0, At, B0); PG8_MMA(1, 1, At, B1); PG8_BAR; PG8_SCHED;
	s_add_i32 s55, 0, 0x18000
	s_add_i32 s56, 0, 0x1c000
	v_add_u32_e32 v140, s55, v167
	v_add_u32_e32 v175, s56, v167
	ds_read_b128 v[128:131], v140
	ds_read_b128 v[132:135], v140 offset:1024
	ds_read_b128 v[136:139], v140 offset:2048
	ds_read_b128 v[140:143], v140 offset:3072
	ds_read_b128 v[160:163], v175
	ds_read_b128 v[176:179], v175 offset:1024
	ds_read_b128 v[180:183], v175 offset:2048
	ds_read_b128 v[184:187], v175 offset:3072
	s_add_u32 s30, s30, 0x40000
	s_addc_u32 s31, s31, 0
	s_mov_b32 m0, s37
	ds_read_b128 v[188:191], v173 offset:32768
	ds_read_b128 v[192:195], v173 offset:33792
	ds_read_b128 v[196:199], v173 offset:34816
	ds_read_b128 v[200:203], v173 offset:35840
	ds_read_b128 v[204:207], v173 offset:36864
	ds_read_b128 v[208:211], v173 offset:37888
	ds_read_b128 v[212:215], v173 offset:38912
	ds_read_b128 v[216:219], v173 offset:39936
	global_load_lds_dwordx4 v144, s[30:31]
	s_mov_b32 m0, s38
	s_nop 0
	global_load_lds_dwordx4 v148, s[30:31]
	s_waitcnt vmcnt(8)
	s_waitcnt lgkmcnt(0)
	s_barrier
	s_setprio 1
	s_waitcnt lgkmcnt(0)
	v_mfma_f32_16x16x32_bf16 v[124:127], v[128:131], v[188:191], v[124:127]
	v_mfma_f32_16x16x32_bf16 v[120:123], v[136:139], v[188:191], v[120:123]
	v_mfma_f32_16x16x32_bf16 v[116:119], v[128:131], v[196:199], v[116:119]
	v_mfma_f32_16x16x32_bf16 v[108:111], v[136:139], v[196:199], v[108:111]
	v_mfma_f32_16x16x32_bf16 v[96:99], v[128:131], v[204:207], v[96:99]
	v_mfma_f32_16x16x32_bf16 v[88:91], v[136:139], v[204:207], v[88:91]
	v_mfma_f32_16x16x32_bf16 v[84:87], v[128:131], v[212:215], v[84:87]
	v_mfma_f32_16x16x32_bf16 v[76:79], v[136:139], v[212:215], v[76:79]
	v_mfma_f32_16x16x32_bf16 v[124:127], v[132:135], v[192:195], v[124:127]
	v_mfma_f32_16x16x32_bf16 v[120:123], v[140:143], v[192:195], v[120:123]
	v_mfma_f32_16x16x32_bf16 v[116:119], v[132:135], v[200:203], v[116:119]
	v_mfma_f32_16x16x32_bf16 v[108:111], v[140:143], v[200:203], v[108:111]
	v_mfma_f32_16x16x32_bf16 v[96:99], v[132:135], v[208:211], v[96:99]
	v_mfma_f32_16x16x32_bf16 v[88:91], v[140:143], v[208:211], v[88:91]
	v_mfma_f32_16x16x32_bf16 v[84:87], v[132:135], v[216:219], v[84:87]
	v_mfma_f32_16x16x32_bf16 v[76:79], v[140:143], v[216:219], v[76:79]
	s_setprio 0
	s_setprio 1
	v_mfma_f32_16x16x32_bf16 v[112:115], v[160:163], v[188:191], v[112:115]
	v_mfma_f32_16x16x32_bf16 v[104:107], v[180:183], v[188:191], v[104:107]
	v_mfma_f32_16x16x32_bf16 v[100:103], v[160:163], v[196:199], v[100:103]
	v_mfma_f32_16x16x32_bf16 v[92:95], v[180:183], v[196:199], v[92:95]
	v_mfma_f32_16x16x32_bf16 v[80:83], v[160:163], v[204:207], v[80:83]
	v_mfma_f32_16x16x32_bf16 v[72:75], v[180:183], v[204:207], v[72:75]
	v_mfma_f32_16x16x32_bf16 v[68:71], v[160:163], v[212:215], v[68:71]
	v_mfma_f32_16x16x32_bf16 v[64:67], v[180:183], v[212:215], v[64:67]
	v_mfma_f32_16x16x32_bf16 v[112:115], v[176:179], v[192:195], v[112:115]
	v_mfma_f32_16x16x32_bf16 v[104:107], v[184:187], v[192:195], v[104:107]
	v_mfma_f32_16x16x32_bf16 v[100:103], v[176:179], v[200:203], v[100:103]
	v_mfma_f32_16x16x32_bf16 v[92:95], v[184:187], v[200:203], v[92:95]
	v_mfma_f32_16x16x32_bf16 v[80:83], v[176:179], v[208:211], v[80:83]
	v_mfma_f32_16x16x32_bf16 v[72:75], v[184:187], v[208:211], v[72:75]
	v_mfma_f32_16x16x32_bf16 v[68:71], v[176:179], v[216:219], v[68:71]
	v_mfma_f32_16x16x32_bf16 v[64:67], v[184:187], v[216:219], v[64:67]
	s_setprio 0
	s_barrier
	s_add_u32 s98, s30, 0xfffc0080
	s_addc_u32 s99, s31, -1
	s_add_u32 s100, s28, 0x80
	s_addc_u32 s101, s29, 0
	s_add_i32 s30, s55, s22
	s_mov_b32 m0, s30
	ds_read_b128 v[188:191], v173 offset:49152
	ds_read_b128 v[192:195], v173 offset:50176
	ds_read_b128 v[196:199], v173 offset:51200
	ds_read_b128 v[200:203], v173 offset:52224
	ds_read_b128 v[204:207], v173 offset:53248
	ds_read_b128 v[208:211], v173 offset:54272
	ds_read_b128 v[212:215], v173 offset:55296
	ds_read_b128 v[216:219], v173 offset:56320
	global_load_lds_dwordx4 v146, s[100:101]
	s_add_i32 m0, s30, 0x2000
	s_add_u32 s28, s28, 0x40080
	s_addc_u32 s29, s29, 0
	s_add_i32 s30, s56, s22
	global_load_lds_dwordx4 v150, s[100:101]
	s_mov_b32 m0, s30
	s_nop 0
	global_load_lds_dwordx4 v146, s[28:29]
	s_add_i32 m0, s30, 0x2000
	s_nop 0
	global_load_lds_dwordx4 v150, s[28:29]
	s_mov_b32 m0, s39
	s_nop 0
	global_load_lds_dwordx4 v144, s[98:99]
	s_mov_b32 m0, s40
	s_nop 0
	global_load_lds_dwordx4 v148, s[98:99]
	s_waitcnt vmcnt(8)
	s_waitcnt lgkmcnt(0)
	s_barrier
	s_setprio 1
	s_waitcnt lgkmcnt(0)
	v_mfma_f32_16x16x32_bf16 v[60:63], v[128:131], v[188:191], v[60:63]
	v_mfma_f32_16x16x32_bf16 v[56:59], v[136:139], v[188:191], v[56:59]
	v_mfma_f32_16x16x32_bf16 v[52:55], v[128:131], v[196:199], v[52:55]
	v_mfma_f32_16x16x32_bf16 v[44:47], v[136:139], v[196:199], v[44:47]
	v_mfma_f32_16x16x32_bf16 v[32:35], v[128:131], v[204:207], v[32:35]
	v_mfma_f32_16x16x32_bf16 v[24:27], v[136:139], v[204:207], v[24:27]
	v_mfma_f32_16x16x32_bf16 v[20:23], v[128:131], v[212:215], v[20:23]
	v_mfma_f32_16x16x32_bf16 v[12:15], v[136:139], v[212:215], v[12:15]
	v_mfma_f32_16x16x32_bf16 v[60:63], v[132:135], v[192:195], v[60:63]
	v_mfma_f32_16x16x32_bf16 v[56:59], v[140:143], v[192:195], v[56:59]
	v_mfma_f32_16x16x32_bf16 v[52:55], v[132:135], v[200:203], v[52:55]
	v_mfma_f32_16x16x32_bf16 v[44:47], v[140:143], v[200:203], v[44:47]
	v_mfma_f32_16x16x32_bf16 v[32:35], v[132:135], v[208:211], v[32:35]
	v_mfma_f32_16x16x32_bf16 v[24:27], v[140:143], v[208:211], v[24:27]
	v_mfma_f32_16x16x32_bf16 v[20:23], v[132:135], v[216:219], v[20:23]
	v_mfma_f32_16x16x32_bf16 v[12:15], v[140:143], v[216:219], v[12:15]
	s_setprio 0
	s_setprio 1
	v_mfma_f32_16x16x32_bf16 v[48:51], v[160:163], v[188:191], v[48:51]
	v_mfma_f32_16x16x32_bf16 v[40:43], v[180:183], v[188:191], v[40:43]
	v_mfma_f32_16x16x32_bf16 v[36:39], v[160:163], v[196:199], v[36:39]
	v_mfma_f32_16x16x32_bf16 v[28:31], v[180:183], v[196:199], v[28:31]
	v_mfma_f32_16x16x32_bf16 v[16:19], v[160:163], v[204:207], v[16:19]
	v_mfma_f32_16x16x32_bf16 v[8:11], v[180:183], v[204:207], v[8:11]
	v_mfma_f32_16x16x32_bf16 v[4:7], v[160:163], v[212:215], v[4:7]
	v_mfma_f32_16x16x32_bf16 v[0:3], v[180:183], v[212:215], v[0:3]
	v_mfma_f32_16x16x32_bf16 v[48:51], v[176:179], v[192:195], v[48:51]
	v_mfma_f32_16x16x32_bf16 v[40:43], v[184:187], v[192:195], v[40:43]
	v_mfma_f32_16x16x32_bf16 v[36:39], v[176:179], v[200:203], v[36:39]
	v_mfma_f32_16x16x32_bf16 v[28:31], v[184:187], v[200:203], v[28:31]
	v_mfma_f32_16x16x32_bf16 v[16:19], v[176:179], v[208:211], v[16:19]
	v_mfma_f32_16x16x32_bf16 v[8:11], v[184:187], v[208:211], v[8:11]
	v_mfma_f32_16x16x32_bf16 v[4:7], v[176:179], v[216:219], v[4:7]
	v_mfma_f32_16x16x32_bf16 v[0:3], v[184:187], v[216:219], v[0:3]
	s_setprio 0
	s_barrier
	s_add_i32 s54, s54, 2
	s_add_u32 s26, s26, 0x100
	s_addc_u32 s27, s27, 0
	s_add_u32 s52, s52, 0x100
	s_addc_u32 s53, s53, 0
	s_cmp_gt_u32 s54, 13
	s_cbranch_scc0 .LBB0_130
	s_and_b64 vcc, exec, s[12:13]
	s_cbranch_vccz .LBB0_133
	s_barrier

; #define PG8_STAGE(bufoff, gbase, voff) do { _Pragma("unroll") for (int _i = 0; _i < 2; ++_i) \
;         __builtin_amdgcn_global_load_lds((const unsigned*)((const char*)(gbase) + (voff)[_i]), (PG8_LAS unsigned*)(lds + (bufoff) + ldsw + _i * 8192), 16, 0, 0); } while (0)
; #define PG8_LDA(dst, b, h) do { _Pragma("unroll") for (int m = 0; m < 4; ++m) _Pragma("unroll") for (int k = 0; k < 2; ++k) dst[m][k] = *(const PG8_LAS bf16x8*)(lds + PG8_SA(b, h) + aoff + m * 2048 + k * 1024); } while (0)
; #define PG8_LDB(dst, b, h) do { _Pragma("unroll") for (int n = 0; n < 2; ++n) _Pragma("unroll") for (int k = 0; k < 2; ++k) dst[n][k] = *(const PG8_LAS bf16x8*)(lds + PG8_SB(b, h) + boff + n * 2048 + k * 1024); } while (0)
; #define PG8_MMA(ai, bj, At, Bt) do { __builtin_amdgcn_s_setprio(1); _Pragma("unroll") for (int m = 0; m < 4; ++m) _Pragma("unroll") for (int n = 0; n < 2; ++n) _Pragma("unroll") for (int k = 0; k < 2; ++k) \
;         acc[ai][bj][m][n] = __builtin_amdgcn_mfma_f32_16x16x32_bf16(Bt[n][k], At[m][k], acc[ai][bj][m][n], 0, 0, 0); __builtin_amdgcn_s_setprio(0); } while (0)
; #define PG8_WAIT_V(n) asm volatile("s_waitcnt vmcnt(" #n ")" ::: "memory")
; #define PG8_WAIT_L(n) asm volatile("s_waitcnt lgkmcnt(" #n ")" ::: "memory")
; #define PG8_BAR __builtin_amdgcn_s_barrier()
; #define PG8_SCHED __builtin_amdgcn_sched_barrier(0)
; template <class Epi, class Sched, bool ALIGN_EPI = false, bool SP2 = false>
; __device__ __forceinline__ void gemm_phase(PG8_LAS unsigned char* lds, const Gemm g, const Sched& S, const Epi& E) {
;     ...
;             PG8_LDB(B0, 0, 0); PG8_LDB(B1, 0, 1); PG8_SCHED; PG8_LDA(At, 0, 0); PG8_STAGE(PG8_SA(1, 1), a1 + hstep, voffA);
;             PG8_WAIT_V(8); PG8_WAIT_L(0); PG8_BAR; PG8_MMA(0, 0, At, B0); PG8_MMA(0, 1, At, B1); PG8_BAR; PG8_SCHED;
;             PG8_LDA(At, 0, 1); PG8_STAGE(PG8_SB(0, 0), b2, voffB); PG8_STAGE(PG8_SB(0, 1), b2 + hstep, voffB); PG8_STAGE(PG8_SA(0, 0), a2, voffA);
;             PG8_WAIT_V(8); PG8_WAIT_L(0); PG8_BAR; PG8_MMA(1, 0, At, B0); PG8_MMA(1, 1, At, B1); PG8_BAR; PG8_SCHED;
.LBB0_658:
	ds_read_b128 v[144:147], v151
	ds_read_b128 v[156:159], v151 offset:1024
	ds_read_b128 v[160:163], v151 offset:2048
	ds_read_b128 v[168:171], v151 offset:3072
	ds_read_b128 v[172:175], v152
	ds_read_b128 v[176:179], v152 offset:1024
	ds_read_b128 v[180:183], v152 offset:2048
	ds_read_b128 v[184:187], v152 offset:3072
	s_add_u32 s26, s24, 0xfffc0080
	s_addc_u32 s27, s25, -1
	s_cmp_eq_u32 s50, 12
	s_cselect_b32 s29, s17, s27
	s_cselect_b32 s28, s23, s26
	s_cselect_b32 s27, s15, s49
	s_cselect_b32 s26, s47, s48
	s_add_i32 m0, s34, 0xc000
	ds_read_b128 v[188:191], v153
	ds_read_b128 v[192:195], v153 offset:1024
	ds_read_b128 v[196:199], v153 offset:2048
	ds_read_b128 v[200:203], v153 offset:3072
	ds_read_b128 v[204:207], v153 offset:4096
	ds_read_b128 v[208:211], v153 offset:5120
	ds_read_b128 v[212:215], v153 offset:6144
	ds_read_b128 v[216:219], v153 offset:7168
	global_load_lds_dwordx4 v136, s[24:25]
	s_add_i32 m0, s34, 0xe000
	s_nop 0
	global_load_lds_dwordx4 v138, s[24:25]
	s_waitcnt vmcnt(8)
	s_waitcnt lgkmcnt(0)
	s_barrier
	s_setprio 1
	s_waitcnt lgkmcnt(0)
	v_mfma_f32_16x16x32_bf16 v[124:127], v[144:147], v[188:191], v[124:127]
	v_mfma_f32_16x16x32_bf16 v[120:123], v[160:163], v[188:191], v[120:123]
	v_mfma_f32_16x16x32_bf16 v[108:111], v[144:147], v[196:199], v[108:111]
	v_mfma_f32_16x16x32_bf16 v[104:107], v[160:163], v[196:199], v[104:107]
	v_mfma_f32_16x16x32_bf16 v[92:95], v[144:147], v[204:207], v[92:95]
	v_mfma_f32_16x16x32_bf16 v[88:91], v[160:163], v[204:207], v[88:91]
	v_mfma_f32_16x16x32_bf16 v[76:79], v[144:147], v[212:215], v[76:79]
	v_mfma_f32_16x16x32_bf16 v[72:75], v[160:163], v[212:215], v[72:75]
	v_mfma_f32_16x16x32_bf16 v[124:127], v[156:159], v[192:195], v[124:127]
	v_mfma_f32_16x16x32_bf16 v[120:123], v[168:171], v[192:195], v[120:123]
	v_mfma_f32_16x16x32_bf16 v[108:111], v[156:159], v[200:203], v[108:111]
	v_mfma_f32_16x16x32_bf16 v[104:107], v[168:171], v[200:203], v[104:107]
	v_mfma_f32_16x16x32_bf16 v[92:95], v[156:159], v[208:211], v[92:95]
	v_mfma_f32_16x16x32_bf16 v[88:91], v[168:171], v[208:211], v[88:91]
	v_mfma_f32_16x16x32_bf16 v[76:79], v[156:159], v[216:219], v[76:79]
	v_mfma_f32_16x16x32_bf16 v[72:75], v[168:171], v[216:219], v[72:75]
	s_setprio 0
	s_setprio 1
	v_mfma_f32_16x16x32_bf16 v[116:119], v[172:175], v[188:191], v[116:119]
	v_mfma_f32_16x16x32_bf16 v[112:115], v[180:183], v[188:191], v[112:115]
	v_mfma_f32_16x16x32_bf16 v[100:103], v[172:175], v[196:199], v[100:103]
	v_mfma_f32_16x16x32_bf16 v[96:99], v[180:183], v[196:199], v[96:99]
	v_mfma_f32_16x16x32_bf16 v[84:87], v[172:175], v[204:207], v[84:87]
	v_mfma_f32_16x16x32_bf16 v[80:83], v[180:183], v[204:207], v[80:83]
	v_mfma_f32_16x16x32_bf16 v[68:71], v[172:175], v[212:215], v[68:71]
	v_mfma_f32_16x16x32_bf16 v[64:67], v[180:183], v[212:215], v[64:67]
	v_mfma_f32_16x16x32_bf16 v[116:119], v[176:179], v[192:195], v[116:119]
	v_mfma_f32_16x16x32_bf16 v[112:115], v[184:187], v[192:195], v[112:115]
	v_mfma_f32_16x16x32_bf16 v[100:103], v[176:179], v[200:203], v[100:103]
	v_mfma_f32_16x16x32_bf16 v[96:99], v[184:187], v[200:203], v[96:99]
	v_mfma_f32_16x16x32_bf16 v[84:87], v[176:179], v[208:211], v[84:87]
	v_mfma_f32_16x16x32_bf16 v[80:83], v[184:187], v[208:211], v[80:83]
	v_mfma_f32_16x16x32_bf16 v[68:71], v[176:179], v[216:219], v[68:71]
	v_mfma_f32_16x16x32_bf16 v[64:67], v[184:187], v[216:219], v[64:67]
	s_setprio 0
	s_barrier
	s_add_i32 s51, s44, s33
	s_mov_b32 m0, s51
	ds_read_b128 v[188:191], v153 offset:16384
	ds_read_b128 v[192:195], v153 offset:17408
	ds_read_b128 v[196:199], v153 offset:18432
	ds_read_b128 v[200:203], v153 offset:19456
	ds_read_b128 v[204:207], v153 offset:20480
	ds_read_b128 v[208:211], v153 offset:21504
	ds_read_b128 v[212:215], v153 offset:22528
	ds_read_b128 v[216:219], v153 offset:23552
	global_load_lds_dwordx4 v130, s[26:27]
	s_add_i32 m0, s51, 0x2000
	s_add_u32 s52, s26, 0x40000
	s_addc_u32 s53, s27, 0
	s_add_i32 s51, s45, s33
	global_load_lds_dwordx4 v134, s[26:27]
	s_mov_b32 m0, s51
	s_nop 0
	global_load_lds_dwordx4 v130, s[52:53]
	s_add_i32 m0, s51, 0x2000
	s_nop 0
	global_load_lds_dwordx4 v134, s[52:53]
	s_mov_b32 m0, s34
	s_nop 0
	global_load_lds_dwordx4 v128, s[28:29]
	s_mov_b32 m0, s35
	s_nop 0
	global_load_lds_dwordx4 v132, s[28:29]
	s_waitcnt vmcnt(8)
	s_waitcnt lgkmcnt(0)
	s_barrier
	s_setprio 1
	s_waitcnt lgkmcnt(0)
	v_mfma_f32_16x16x32_bf16 v[60:63], v[144:147], v[188:191], v[60:63]
	v_mfma_f32_16x16x32_bf16 v[56:59], v[160:163], v[188:191], v[56:59]
	v_mfma_f32_16x16x32_bf16 v[44:47], v[144:147], v[196:199], v[44:47]
	v_mfma_f32_16x16x32_bf16 v[40:43], v[160:163], v[196:199], v[40:43]
	v_mfma_f32_16x16x32_bf16 v[28:31], v[144:147], v[204:207], v[28:31]
	v_mfma_f32_16x16x32_bf16 v[24:27], v[160:163], v[204:207], v[24:27]
	v_mfma_f32_16x16x32_bf16 v[12:15], v[144:147], v[212:215], v[12:15]
	v_mfma_f32_16x16x32_bf16 v[8:11], v[160:163], v[212:215], v[8:11]
	v_mfma_f32_16x16x32_bf16 v[60:63], v[156:159], v[192:195], v[60:63]
	v_mfma_f32_16x16x32_bf16 v[56:59], v[168:171], v[192:195], v[56:59]
	v_mfma_f32_16x16x32_bf16 v[44:47], v[156:159], v[200:203], v[44:47]
	v_mfma_f32_16x16x32_bf16 v[40:43], v[168:171], v[200:203], v[40:43]
	v_mfma_f32_16x16x32_bf16 v[28:31], v[156:159], v[208:211], v[28:31]
	v_mfma_f32_16x16x32_bf16 v[24:27], v[168:171], v[208:211], v[24:27]
	v_mfma_f32_16x16x32_bf16 v[12:15], v[156:159], v[216:219], v[12:15]
	v_mfma_f32_16x16x32_bf16 v[8:11], v[168:171], v[216:219], v[8:11]
	s_setprio 0
	s_setprio 1
	v_mfma_f32_16x16x32_bf16 v[52:55], v[172:175], v[188:191], v[52:55]
	v_mfma_f32_16x16x32_bf16 v[48:51], v[180:183], v[188:191], v[48:51]
	v_mfma_f32_16x16x32_bf16 v[36:39], v[172:175], v[196:199], v[36:39]
	v_mfma_f32_16x16x32_bf16 v[32:35], v[180:183], v[196:199], v[32:35]
	v_mfma_f32_16x16x32_bf16 v[20:23], v[172:175], v[204:207], v[20:23]
	v_mfma_f32_16x16x32_bf16 v[16:19], v[180:183], v[204:207], v[16:19]
	v_mfma_f32_16x16x32_bf16 v[4:7], v[172:175], v[212:215], v[4:7]
	v_mfma_f32_16x16x32_bf16 v[0:3], v[180:183], v[212:215], v[0:3]
	v_mfma_f32_16x16x32_bf16 v[52:55], v[176:179], v[192:195], v[52:55]
	v_mfma_f32_16x16x32_bf16 v[48:51], v[184:187], v[192:195], v[48:51]
	v_mfma_f32_16x16x32_bf16 v[36:39], v[176:179], v[200:203], v[36:39]
	v_mfma_f32_16x16x32_bf16 v[32:35], v[184:187], v[200:203], v[32:35]
	v_mfma_f32_16x16x32_bf16 v[20:23], v[176:179], v[208:211], v[20:23]
	v_mfma_f32_16x16x32_bf16 v[16:19], v[184:187], v[208:211], v[16:19]
	v_mfma_f32_16x16x32_bf16 v[4:7], v[176:179], v[216:219], v[4:7]
	v_mfma_f32_16x16x32_bf16 v[0:3], v[184:187], v[216:219], v[0:3]
	s_setprio 0
	s_barrier
; #define PG8_STAGE(bufoff, gbase, voff) do { _Pragma("unroll") for (int _i = 0; _i < 2; ++_i) \
;         __builtin_amdgcn_global_load_lds((const unsigned*)((const char*)(gbase) + (voff)[_i]), (PG8_LAS unsigned*)(lds + (bufoff) + ldsw + _i * 8192), 16, 0, 0); } while (0)
; #define PG8_LDA(dst, b, h) do { _Pragma("unroll") for (int m = 0; m < 4; ++m) _Pragma("unroll") for (int k = 0; k < 2; ++k) dst[m][k] = *(const PG8_LAS bf16x8*)(lds + PG8_SA(b, h) + aoff + m * 2048 + k * 1024); } while (0)
; #define PG8_LDB(dst, b, h) do { _Pragma("unroll") for (int n = 0; n < 2; ++n) _Pragma("unroll") for (int k = 0; k < 2; ++k) dst[n][k] = *(const PG8_LAS bf16x8*)(lds + PG8_SB(b, h) + boff + n * 2048 + k * 1024); } while (0)
; #define PG8_MMA(ai, bj, At, Bt) do { __builtin_amdgcn_s_setprio(1); _Pragma("unroll") for (int m = 0; m < 4; ++m) _Pragma("unroll") for (int n = 0; n < 2; ++n) _Pragma("unroll") for (int k = 0; k < 2; ++k) \
;         acc[ai][bj][m][n] = __builtin_amdgcn_mfma_f32_16x16x32_bf16(Bt[n][k], At[m][k], acc[ai][bj][m][n], 0, 0, 0); __builtin_amdgcn_s_setprio(0); } while (0)
; #define PG8_WAIT_V(n) asm volatile("s_waitcnt vmcnt(" #n ")" ::: "memory")
; #define PG8_WAIT_L(n) asm volatile("s_waitcnt lgkmcnt(" #n ")" ::: "memory")
; #define PG8_BAR __builtin_amdgcn_s_barrier()
; #define PG8_SCHED __builtin_amdgcn_sched_barrier(0)
; template <class Epi, class Sched, bool ALIGN_EPI = false, bool SP2 = false>
; __device__ __forceinline__ void gemm_phase(PG8_LAS unsigned char* lds, const Gemm g, const Sched& S, const Epi& E) {
;     ...
;             PG8_LDB(B0, 1, 0); PG8_LDB(B1, 1, 1); PG8_SCHED; PG8_LDA(At, 1, 0); PG8_STAGE(PG8_SA(0, 1), a2 + hstep, voffA);
;             PG8_WAIT_V(8); PG8_WAIT_L(0); PG8_BAR; PG8_MMA(0, 0, At, B0); PG8_MMA(0, 1, At, B1); PG8_BAR; PG8_SCHED;
	s_add_i32 s51, 0, 0x18000
	v_add_u32_e32 v155, s51, v149
	s_add_i32 s52, 0, 0x1c000
	ds_read_b128 v[144:147], v155
	ds_read_b128 v[156:159], v155 offset:1024
	ds_read_b128 v[160:163], v155 offset:2048
	ds_read_b128 v[168:171], v155 offset:3072
	v_add_u32_e32 v155, s52, v149
	ds_read_b128 v[172:175], v155
	ds_read_b128 v[176:179], v155 offset:1024
	ds_read_b128 v[180:183], v155 offset:2048
	ds_read_b128 v[184:187], v155 offset:3072
	s_add_u32 s28, s28, 0x40000
	s_addc_u32 s29, s29, 0
	s_mov_b32 m0, s36
	ds_read_b128 v[188:191], v153 offset:32768
	ds_read_b128 v[192:195], v153 offset:33792
	ds_read_b128 v[196:199], v153 offset:34816
	ds_read_b128 v[200:203], v153 offset:35840
	ds_read_b128 v[204:207], v153 offset:36864
	ds_read_b128 v[208:211], v153 offset:37888
	ds_read_b128 v[212:215], v153 offset:38912
	ds_read_b128 v[216:219], v153 offset:39936
	global_load_lds_dwordx4 v128, s[28:29]
	s_mov_b32 m0, s37
	s_nop 0
	global_load_lds_dwordx4 v132, s[28:29]
	s_waitcnt vmcnt(8)
	s_waitcnt lgkmcnt(0)
	s_barrier
	s_setprio 1
	s_waitcnt lgkmcnt(0)
	v_mfma_f32_16x16x32_bf16 v[124:127], v[144:147], v[188:191], v[124:127]
	v_mfma_f32_16x16x32_bf16 v[120:123], v[160:163], v[188:191], v[120:123]
	v_mfma_f32_16x16x32_bf16 v[108:111], v[144:147], v[196:199], v[108:111]
	v_mfma_f32_16x16x32_bf16 v[104:107], v[160:163], v[196:199], v[104:107]
	v_mfma_f32_16x16x32_bf16 v[92:95], v[144:147], v[204:207], v[92:95]
	v_mfma_f32_16x16x32_bf16 v[88:91], v[160:163], v[204:207], v[88:91]
	v_mfma_f32_16x16x32_bf16 v[76:79], v[144:147], v[212:215], v[76:79]
	v_mfma_f32_16x16x32_bf16 v[72:75], v[160:163], v[212:215], v[72:75]
	v_mfma_f32_16x16x32_bf16 v[124:127], v[156:159], v[192:195], v[124:127]
	v_mfma_f32_16x16x32_bf16 v[120:123], v[168:171], v[192:195], v[120:123]
	v_mfma_f32_16x16x32_bf16 v[108:111], v[156:159], v[200:203], v[108:111]
	v_mfma_f32_16x16x32_bf16 v[104:107], v[168:171], v[200:203], v[104:107]
	v_mfma_f32_16x16x32_bf16 v[92:95], v[156:159], v[208:211], v[92:95]
	v_mfma_f32_16x16x32_bf16 v[88:91], v[168:171], v[208:211], v[88:91]
	v_mfma_f32_16x16x32_bf16 v[76:79], v[156:159], v[216:219], v[76:79]
	v_mfma_f32_16x16x32_bf16 v[72:75], v[168:171], v[216:219], v[72:75]
	s_setprio 0
	s_setprio 1
	v_mfma_f32_16x16x32_bf16 v[116:119], v[172:175], v[188:191], v[116:119]
	v_mfma_f32_16x16x32_bf16 v[112:115], v[180:183], v[188:191], v[112:115]
	v_mfma_f32_16x16x32_bf16 v[100:103], v[172:175], v[196:199], v[100:103]
	v_mfma_f32_16x16x32_bf16 v[96:99], v[180:183], v[196:199], v[96:99]
	v_mfma_f32_16x16x32_bf16 v[84:87], v[172:175], v[204:207], v[84:87]
	v_mfma_f32_16x16x32_bf16 v[80:83], v[180:183], v[204:207], v[80:83]
	v_mfma_f32_16x16x32_bf16 v[68:71], v[172:175], v[212:215], v[68:71]
	v_mfma_f32_16x16x32_bf16 v[64:67], v[180:183], v[212:215], v[64:67]
	v_mfma_f32_16x16x32_bf16 v[116:119], v[176:179], v[192:195], v[116:119]
	v_mfma_f32_16x16x32_bf16 v[112:115], v[184:187], v[192:195], v[112:115]
	v_mfma_f32_16x16x32_bf16 v[100:103], v[176:179], v[200:203], v[100:103]
	v_mfma_f32_16x16x32_bf16 v[96:99], v[184:187], v[200:203], v[96:99]
	v_mfma_f32_16x16x32_bf16 v[84:87], v[176:179], v[208:211], v[84:87]
	v_mfma_f32_16x16x32_bf16 v[80:83], v[184:187], v[208:211], v[80:83]
	v_mfma_f32_16x16x32_bf16 v[68:71], v[176:179], v[216:219], v[68:71]
	v_mfma_f32_16x16x32_bf16 v[64:67], v[184:187], v[216:219], v[64:67]
	s_setprio 0
	s_barrier
; #define PG8_STAGE(bufoff, gbase, voff) do { _Pragma("unroll") for (int _i = 0; _i < 2; ++_i) \
;         __builtin_amdgcn_global_load_lds((const unsigned*)((const char*)(gbase) + (voff)[_i]), (PG8_LAS unsigned*)(lds + (bufoff) + ldsw + _i * 8192), 16, 0, 0); } while (0)
; #define PG8_LDA(dst, b, h) do { _Pragma("unroll") for (int m = 0; m < 4; ++m) _Pragma("unroll") for (int k = 0; k < 2; ++k) dst[m][k] = *(const PG8_LAS bf16x8*)(lds + PG8_SA(b, h) + aoff + m * 2048 + k * 1024); } while (0)
; #define PG8_MMA(ai, bj, At, Bt) do { __builtin_amdgcn_s_setprio(1); _Pragma("unroll") for (int m = 0; m < 4; ++m) _Pragma("unroll") for (int n = 0; n < 2; ++n) _Pragma("unroll") for (int k = 0; k < 2; ++k) \
;         acc[ai][bj][m][n] = __builtin_amdgcn_mfma_f32_16x16x32_bf16(Bt[n][k], At[m][k], acc[ai][bj][m][n], 0, 0, 0); __builtin_amdgcn_s_setprio(0); } while (0)
; #define PG8_WAIT_V(n) asm volatile("s_waitcnt vmcnt(" #n ")" ::: "memory")
; #define PG8_WAIT_L(n) asm volatile("s_waitcnt lgkmcnt(" #n ")" ::: "memory")
; #define PG8_BAR __builtin_amdgcn_s_barrier()
; #define PG8_SCHED __builtin_amdgcn_sched_barrier(0)
; template <class Epi, class Sched, bool ALIGN_EPI = false, bool SP2 = false>
; __device__ __forceinline__ void gemm_phase(PG8_LAS unsigned char* lds, const Gemm g, const Sched& S, const Epi& E) {
;     ...
;         for (int t = 0; t < nt; t += 2) {
;             const bool last = (t == nt - 2);
;     ...
;             PG8_LDA(At, 1, 1); PG8_STAGE(PG8_SB(1, 0), b3, voffB); PG8_STAGE(PG8_SB(1, 1), b3 + hstep, voffB); PG8_STAGE(PG8_SA(1, 0), a3, voffA);
;             PG8_WAIT_V(8); PG8_WAIT_L(0); PG8_BAR; PG8_MMA(1, 0, At, B0); PG8_MMA(1, 1, At, B1); PG8_BAR; PG8_SCHED;
	s_add_u32 s98, s28, 0xfffc0080
	s_addc_u32 s99, s29, -1
	s_add_u32 s100, s26, 0x80
	s_addc_u32 s101, s27, 0
	s_add_i32 s28, s51, s33
	s_mov_b32 m0, s28
	ds_read_b128 v[188:191], v153 offset:49152
	ds_read_b128 v[192:195], v153 offset:50176
	ds_read_b128 v[196:199], v153 offset:51200
	ds_read_b128 v[200:203], v153 offset:52224
	ds_read_b128 v[204:207], v153 offset:53248
	ds_read_b128 v[208:211], v153 offset:54272
	ds_read_b128 v[212:215], v153 offset:55296
	ds_read_b128 v[216:219], v153 offset:56320
	global_load_lds_dwordx4 v130, s[100:101]
	s_add_i32 m0, s28, 0x2000
	s_add_u32 s26, s26, 0x40080
	s_addc_u32 s27, s27, 0
	s_add_i32 s28, s52, s33
	global_load_lds_dwordx4 v134, s[100:101]
	s_mov_b32 m0, s28
	s_nop 0
	global_load_lds_dwordx4 v130, s[26:27]
	s_add_i32 m0, s28, 0x2000
	s_nop 0
	global_load_lds_dwordx4 v134, s[26:27]
	s_mov_b32 m0, s39
	s_nop 0
	global_load_lds_dwordx4 v128, s[98:99]
	s_mov_b32 m0, s40
	s_nop 0
	global_load_lds_dwordx4 v132, s[98:99]
	s_waitcnt vmcnt(8)
	s_waitcnt lgkmcnt(0)
	s_barrier
	s_setprio 1
	s_waitcnt lgkmcnt(0)
	v_mfma_f32_16x16x32_bf16 v[60:63], v[144:147], v[188:191], v[60:63]
	v_mfma_f32_16x16x32_bf16 v[56:59], v[160:163], v[188:191], v[56:59]
	v_mfma_f32_16x16x32_bf16 v[44:47], v[144:147], v[196:199], v[44:47]
	v_mfma_f32_16x16x32_bf16 v[40:43], v[160:163], v[196:199], v[40:43]
	v_mfma_f32_16x16x32_bf16 v[28:31], v[144:147], v[204:207], v[28:31]
	v_mfma_f32_16x16x32_bf16 v[24:27], v[160:163], v[204:207], v[24:27]
	v_mfma_f32_16x16x32_bf16 v[12:15], v[144:147], v[212:215], v[12:15]
	v_mfma_f32_16x16x32_bf16 v[8:11], v[160:163], v[212:215], v[8:11]
	v_mfma_f32_16x16x32_bf16 v[60:63], v[156:159], v[192:195], v[60:63]
	v_mfma_f32_16x16x32_bf16 v[56:59], v[168:171], v[192:195], v[56:59]
	v_mfma_f32_16x16x32_bf16 v[44:47], v[156:159], v[200:203], v[44:47]
	v_mfma_f32_16x16x32_bf16 v[40:43], v[168:171], v[200:203], v[40:43]
	v_mfma_f32_16x16x32_bf16 v[28:31], v[156:159], v[208:211], v[28:31]
	v_mfma_f32_16x16x32_bf16 v[24:27], v[168:171], v[208:211], v[24:27]
	v_mfma_f32_16x16x32_bf16 v[12:15], v[156:159], v[216:219], v[12:15]
	v_mfma_f32_16x16x32_bf16 v[8:11], v[168:171], v[216:219], v[8:11]
	s_setprio 0
	s_setprio 1
	v_mfma_f32_16x16x32_bf16 v[52:55], v[172:175], v[188:191], v[52:55]
	v_mfma_f32_16x16x32_bf16 v[48:51], v[180:183], v[188:191], v[48:51]
	v_mfma_f32_16x16x32_bf16 v[36:39], v[172:175], v[196:199], v[36:39]
	v_mfma_f32_16x16x32_bf16 v[32:35], v[180:183], v[196:199], v[32:35]
	v_mfma_f32_16x16x32_bf16 v[20:23], v[172:175], v[204:207], v[20:23]
	v_mfma_f32_16x16x32_bf16 v[16:19], v[180:183], v[204:207], v[16:19]
	v_mfma_f32_16x16x32_bf16 v[4:7], v[172:175], v[212:215], v[4:7]
	v_mfma_f32_16x16x32_bf16 v[0:3], v[180:183], v[212:215], v[0:3]
	v_mfma_f32_16x16x32_bf16 v[52:55], v[176:179], v[192:195], v[52:55]
	v_mfma_f32_16x16x32_bf16 v[48:51], v[184:187], v[192:195], v[48:51]
	v_mfma_f32_16x16x32_bf16 v[36:39], v[176:179], v[200:203], v[36:39]
	v_mfma_f32_16x16x32_bf16 v[32:35], v[184:187], v[200:203], v[32:35]
	v_mfma_f32_16x16x32_bf16 v[20:23], v[176:179], v[208:211], v[20:23]
	v_mfma_f32_16x16x32_bf16 v[16:19], v[184:187], v[208:211], v[16:19]
	v_mfma_f32_16x16x32_bf16 v[4:7], v[176:179], v[216:219], v[4:7]
	v_mfma_f32_16x16x32_bf16 v[0:3], v[184:187], v[216:219], v[0:3]
	s_setprio 0
	s_barrier
	s_add_i32 s50, s50, 2
	s_add_u32 s24, s24, 0x100
	s_addc_u32 s25, s25, 0
	s_add_u32 s48, s48, 0x100
	s_addc_u32 s49, s49, 0
	s_cmp_gt_u32 s50, 13
	s_cbranch_scc0 .LBB0_658
	v_mbcnt_lo_u32_b32 v234, -1, 0
	v_mbcnt_hi_u32_b32 v234, -1, v234
	v_bfe_u32 v234, v234, 3, 1
	v_sub_u32_e32 v231, 0, v234
	v_and_b32_e32 v230, 0xffff8010, v231
	v_and_b32_e32 v235, 0x7ff0, v231
	v_sub_u32_e32 v244, 0x8000, v235
	v_mov_b32_e32 v245, 0
	s_mov_b32 s98, 0xff00ff
	s_mov_b32 s99, 0xff00ff
	s_and_b64 vcc, exec, s[12:13]
	s_cbranch_vccz .LBB0_661
	s_barrier

; #define PG8_STAGE(bufoff, gbase, voff) do { _Pragma("unroll") for (int _i = 0; _i < 2; ++_i) \
;         __builtin_amdgcn_global_load_lds((const unsigned*)((const char*)(gbase) + (voff)[_i]), (PG8_LAS unsigned*)(lds + (bufoff) + ldsw + _i * 8192), 16, 0, 0); } while (0)
; #define PG8_LDA(dst, b, h) do { _Pragma("unroll") for (int m = 0; m < 4; ++m) _Pragma("unroll") for (int k = 0; k < 2; ++k) dst[m][k] = *(const PG8_LAS bf16x8*)(lds + PG8_SA(b, h) + aoff + m * 2048 + k * 1024); } while (0)
; #define PG8_LDB(dst, b, h) do { _Pragma("unroll") for (int n = 0; n < 2; ++n) _Pragma("unroll") for (int k = 0; k < 2; ++k) dst[n][k] = *(const PG8_LAS bf16x8*)(lds + PG8_SB(b, h) + boff + n * 2048 + k * 1024); } while (0)
; #define PG8_MMA(ai, bj, At, Bt) do { __builtin_amdgcn_s_setprio(1); _Pragma("unroll") for (int m = 0; m < 4; ++m) _Pragma("unroll") for (int n = 0; n < 2; ++n) _Pragma("unroll") for (int k = 0; k < 2; ++k) \
;         acc[ai][bj][m][n] = __builtin_amdgcn_mfma_f32_16x16x32_bf16(Bt[n][k], At[m][k], acc[ai][bj][m][n], 0, 0, 0); __builtin_amdgcn_s_setprio(0); } while (0)
; #define PG8_WAIT_V(n) asm volatile("s_waitcnt vmcnt(" #n ")" ::: "memory")
; #define PG8_WAIT_L(n) asm volatile("s_waitcnt lgkmcnt(" #n ")" ::: "memory")
; #define PG8_BAR __builtin_amdgcn_s_barrier()
; #define PG8_SCHED __builtin_amdgcn_sched_barrier(0)
; template <class Epi, class Sched, bool ALIGN_EPI = false, bool SP2 = false>
; __device__ __forceinline__ void gemm_phase(PG8_LAS unsigned char* lds, const Gemm g, const Sched& S, const Epi& E) {
;     ...
;             PG8_LDB(B0, 0, 0); PG8_LDB(B1, 0, 1); PG8_SCHED; PG8_LDA(At, 0, 0); PG8_STAGE(PG8_SA(1, 1), a1 + hstep, voffA);
;             PG8_WAIT_V(8); PG8_WAIT_L(0); PG8_BAR; PG8_MMA(0, 0, At, B0); PG8_MMA(0, 1, At, B1); PG8_BAR; PG8_SCHED;
;             PG8_LDA(At, 0, 1); PG8_STAGE(PG8_SB(0, 0), b2, voffB); PG8_STAGE(PG8_SB(0, 1), b2 + hstep, voffB); PG8_STAGE(PG8_SA(0, 0), a2, voffA);
;             PG8_WAIT_V(8); PG8_WAIT_L(0); PG8_BAR; PG8_MMA(1, 0, At, B0); PG8_MMA(1, 1, At, B1); PG8_BAR; PG8_SCHED;
.LBB0_755:
	ds_read_b128 v[128:131], v173
	ds_read_b128 v[132:135], v173 offset:1024
	ds_read_b128 v[136:139], v173 offset:2048
	ds_read_b128 v[140:143], v173 offset:3072
	ds_read_b128 v[160:163], v174
	ds_read_b128 v[178:181], v174 offset:1024
	ds_read_b128 v[182:185], v174 offset:2048
	ds_read_b128 v[186:189], v174 offset:3072
	s_add_u32 s38, s36, 0xfffc0080
	s_addc_u32 s39, s37, -1
	s_cmp_eq_u32 s63, 12
	s_cselect_b32 s41, s25, s39
	s_cselect_b32 s40, s59, s38
	s_cselect_b32 s39, s23, s62
	s_cselect_b32 s38, s60, s61
	s_add_i32 m0, s35, 0xc000
	ds_read_b128 v[190:193], v175
	ds_read_b128 v[194:197], v175 offset:1024
	ds_read_b128 v[198:201], v175 offset:2048
	ds_read_b128 v[202:205], v175 offset:3072
	ds_read_b128 v[206:209], v175 offset:4096
	ds_read_b128 v[210:213], v175 offset:5120
	ds_read_b128 v[214:217], v175 offset:6144
	ds_read_b128 v[218:221], v175 offset:7168
	global_load_lds_dwordx4 v152, s[36:37]
	s_add_i32 m0, s35, 0xe000
	s_nop 0
	global_load_lds_dwordx4 v154, s[36:37]
	s_waitcnt vmcnt(8)
	s_waitcnt lgkmcnt(0)
	s_barrier
	s_setprio 1
	s_waitcnt lgkmcnt(0)
	v_mfma_f32_16x16x32_bf16 v[124:127], v[128:131], v[190:193], v[124:127]
	v_mfma_f32_16x16x32_bf16 v[120:123], v[136:139], v[190:193], v[120:123]
	v_mfma_f32_16x16x32_bf16 v[108:111], v[128:131], v[198:201], v[108:111]
	v_mfma_f32_16x16x32_bf16 v[104:107], v[136:139], v[198:201], v[104:107]
	v_mfma_f32_16x16x32_bf16 v[92:95], v[128:131], v[206:209], v[92:95]
	v_mfma_f32_16x16x32_bf16 v[88:91], v[136:139], v[206:209], v[88:91]
	v_mfma_f32_16x16x32_bf16 v[76:79], v[128:131], v[214:217], v[76:79]
	v_mfma_f32_16x16x32_bf16 v[72:75], v[136:139], v[214:217], v[72:75]
	v_mfma_f32_16x16x32_bf16 v[124:127], v[132:135], v[194:197], v[124:127]
	v_mfma_f32_16x16x32_bf16 v[120:123], v[140:143], v[194:197], v[120:123]
	v_mfma_f32_16x16x32_bf16 v[108:111], v[132:135], v[202:205], v[108:111]
	v_mfma_f32_16x16x32_bf16 v[104:107], v[140:143], v[202:205], v[104:107]
	v_mfma_f32_16x16x32_bf16 v[92:95], v[132:135], v[210:213], v[92:95]
	v_mfma_f32_16x16x32_bf16 v[88:91], v[140:143], v[210:213], v[88:91]
	v_mfma_f32_16x16x32_bf16 v[76:79], v[132:135], v[218:221], v[76:79]
	v_mfma_f32_16x16x32_bf16 v[72:75], v[140:143], v[218:221], v[72:75]
	s_setprio 0
	s_setprio 1
	v_mfma_f32_16x16x32_bf16 v[116:119], v[160:163], v[190:193], v[116:119]
	v_mfma_f32_16x16x32_bf16 v[112:115], v[182:185], v[190:193], v[112:115]
	v_mfma_f32_16x16x32_bf16 v[100:103], v[160:163], v[198:201], v[100:103]
	v_mfma_f32_16x16x32_bf16 v[96:99], v[182:185], v[198:201], v[96:99]
	v_mfma_f32_16x16x32_bf16 v[84:87], v[160:163], v[206:209], v[84:87]
	v_mfma_f32_16x16x32_bf16 v[80:83], v[182:185], v[206:209], v[80:83]
	v_mfma_f32_16x16x32_bf16 v[68:71], v[160:163], v[214:217], v[68:71]
	v_mfma_f32_16x16x32_bf16 v[64:67], v[182:185], v[214:217], v[64:67]
	v_mfma_f32_16x16x32_bf16 v[116:119], v[178:181], v[194:197], v[116:119]
	v_mfma_f32_16x16x32_bf16 v[112:115], v[186:189], v[194:197], v[112:115]
	v_mfma_f32_16x16x32_bf16 v[100:103], v[178:181], v[202:205], v[100:103]
	v_mfma_f32_16x16x32_bf16 v[96:99], v[186:189], v[202:205], v[96:99]
	v_mfma_f32_16x16x32_bf16 v[84:87], v[178:181], v[210:213], v[84:87]
	v_mfma_f32_16x16x32_bf16 v[80:83], v[186:189], v[210:213], v[80:83]
	v_mfma_f32_16x16x32_bf16 v[68:71], v[178:181], v[218:221], v[68:71]
	v_mfma_f32_16x16x32_bf16 v[64:67], v[186:189], v[218:221], v[64:67]
	s_setprio 0
	s_barrier
	s_add_i32 s64, s51, s30
	s_mov_b32 m0, s64
	ds_read_b128 v[190:193], v175 offset:16384
	ds_read_b128 v[194:197], v175 offset:17408
	ds_read_b128 v[198:201], v175 offset:18432
	ds_read_b128 v[202:205], v175 offset:19456
	ds_read_b128 v[206:209], v175 offset:20480
	ds_read_b128 v[210:213], v175 offset:21504
	ds_read_b128 v[214:217], v175 offset:22528
	ds_read_b128 v[218:221], v175 offset:23552
	global_load_lds_dwordx4 v146, s[38:39]
	s_add_i32 m0, s64, 0x2000
	s_add_u32 s64, s38, 0x40000
	s_addc_u32 s65, s39, 0
	s_add_i32 s66, s52, s30
	global_load_lds_dwordx4 v150, s[38:39]
	s_mov_b32 m0, s66
	s_nop 0
	global_load_lds_dwordx4 v146, s[64:65]
	s_add_i32 m0, s66, 0x2000
	s_nop 0
	global_load_lds_dwordx4 v150, s[64:65]
	s_mov_b32 m0, s35
	s_nop 0
	global_load_lds_dwordx4 v144, s[40:41]
	s_mov_b32 m0, s44
	s_nop 0
	global_load_lds_dwordx4 v148, s[40:41]
	s_waitcnt vmcnt(8)
	s_waitcnt lgkmcnt(0)
	s_barrier
	s_setprio 1
	s_waitcnt lgkmcnt(0)
	v_mfma_f32_16x16x32_bf16 v[60:63], v[128:131], v[190:193], v[60:63]
	v_mfma_f32_16x16x32_bf16 v[56:59], v[136:139], v[190:193], v[56:59]
	v_mfma_f32_16x16x32_bf16 v[44:47], v[128:131], v[198:201], v[44:47]
	v_mfma_f32_16x16x32_bf16 v[40:43], v[136:139], v[198:201], v[40:43]
	v_mfma_f32_16x16x32_bf16 v[28:31], v[128:131], v[206:209], v[28:31]
	v_mfma_f32_16x16x32_bf16 v[24:27], v[136:139], v[206:209], v[24:27]
	v_mfma_f32_16x16x32_bf16 v[12:15], v[128:131], v[214:217], v[12:15]
	v_mfma_f32_16x16x32_bf16 v[8:11], v[136:139], v[214:217], v[8:11]
	v_mfma_f32_16x16x32_bf16 v[60:63], v[132:135], v[194:197], v[60:63]
	v_mfma_f32_16x16x32_bf16 v[56:59], v[140:143], v[194:197], v[56:59]
	v_mfma_f32_16x16x32_bf16 v[44:47], v[132:135], v[202:205], v[44:47]
	v_mfma_f32_16x16x32_bf16 v[40:43], v[140:143], v[202:205], v[40:43]
	v_mfma_f32_16x16x32_bf16 v[28:31], v[132:135], v[210:213], v[28:31]
	v_mfma_f32_16x16x32_bf16 v[24:27], v[140:143], v[210:213], v[24:27]
	v_mfma_f32_16x16x32_bf16 v[12:15], v[132:135], v[218:221], v[12:15]
	v_mfma_f32_16x16x32_bf16 v[8:11], v[140:143], v[218:221], v[8:11]
	s_setprio 0
	s_setprio 1
	v_mfma_f32_16x16x32_bf16 v[52:55], v[160:163], v[190:193], v[52:55]
	v_mfma_f32_16x16x32_bf16 v[48:51], v[182:185], v[190:193], v[48:51]
	v_mfma_f32_16x16x32_bf16 v[36:39], v[160:163], v[198:201], v[36:39]
	v_mfma_f32_16x16x32_bf16 v[32:35], v[182:185], v[198:201], v[32:35]
	v_mfma_f32_16x16x32_bf16 v[20:23], v[160:163], v[206:209], v[20:23]
	v_mfma_f32_16x16x32_bf16 v[16:19], v[182:185], v[206:209], v[16:19]
	v_mfma_f32_16x16x32_bf16 v[4:7], v[160:163], v[214:217], v[4:7]
	v_mfma_f32_16x16x32_bf16 v[0:3], v[182:185], v[214:217], v[0:3]
	v_mfma_f32_16x16x32_bf16 v[52:55], v[178:181], v[194:197], v[52:55]
	v_mfma_f32_16x16x32_bf16 v[48:51], v[186:189], v[194:197], v[48:51]
	v_mfma_f32_16x16x32_bf16 v[36:39], v[178:181], v[202:205], v[36:39]
	v_mfma_f32_16x16x32_bf16 v[32:35], v[186:189], v[202:205], v[32:35]
	v_mfma_f32_16x16x32_bf16 v[20:23], v[178:181], v[210:213], v[20:23]
	v_mfma_f32_16x16x32_bf16 v[16:19], v[186:189], v[210:213], v[16:19]
	v_mfma_f32_16x16x32_bf16 v[4:7], v[178:181], v[218:221], v[4:7]
	v_mfma_f32_16x16x32_bf16 v[0:3], v[186:189], v[218:221], v[0:3]
	s_setprio 0
	s_barrier
; #define PG8_STAGE(bufoff, gbase, voff) do { _Pragma("unroll") for (int _i = 0; _i < 2; ++_i) \
;         __builtin_amdgcn_global_load_lds((const unsigned*)((const char*)(gbase) + (voff)[_i]), (PG8_LAS unsigned*)(lds + (bufoff) + ldsw + _i * 8192), 16, 0, 0); } while (0)
; #define PG8_LDA(dst, b, h) do { _Pragma("unroll") for (int m = 0; m < 4; ++m) _Pragma("unroll") for (int k = 0; k < 2; ++k) dst[m][k] = *(const PG8_LAS bf16x8*)(lds + PG8_SA(b, h) + aoff + m * 2048 + k * 1024); } while (0)
; #define PG8_LDB(dst, b, h) do { _Pragma("unroll") for (int n = 0; n < 2; ++n) _Pragma("unroll") for (int k = 0; k < 2; ++k) dst[n][k] = *(const PG8_LAS bf16x8*)(lds + PG8_SB(b, h) + boff + n * 2048 + k * 1024); } while (0)
; #define PG8_MMA(ai, bj, At, Bt) do { __builtin_amdgcn_s_setprio(1); _Pragma("unroll") for (int m = 0; m < 4; ++m) _Pragma("unroll") for (int n = 0; n < 2; ++n) _Pragma("unroll") for (int k = 0; k < 2; ++k) \
;         acc[ai][bj][m][n] = __builtin_amdgcn_mfma_f32_16x16x32_bf16(Bt[n][k], At[m][k], acc[ai][bj][m][n], 0, 0, 0); __builtin_amdgcn_s_setprio(0); } while (0)
; #define PG8_WAIT_V(n) asm volatile("s_waitcnt vmcnt(" #n ")" ::: "memory")
; #define PG8_WAIT_L(n) asm volatile("s_waitcnt lgkmcnt(" #n ")" ::: "memory")
; #define PG8_BAR __builtin_amdgcn_s_barrier()
; #define PG8_SCHED __builtin_amdgcn_sched_barrier(0)
; template <class Epi, class Sched, bool ALIGN_EPI = false, bool SP2 = false>
; __device__ __forceinline__ void gemm_phase(PG8_LAS unsigned char* lds, const Gemm g, const Sched& S, const Epi& E) {
;     ...
;             PG8_LDB(B0, 1, 0); PG8_LDB(B1, 1, 1); PG8_SCHED; PG8_LDA(At, 1, 0); PG8_STAGE(PG8_SA(0, 1), a2 + hstep, voffA);
;             PG8_WAIT_V(8); PG8_WAIT_L(0); PG8_BAR; PG8_MMA(0, 0, At, B0); PG8_MMA(0, 1, At, B1); PG8_BAR; PG8_SCHED;
;             PG8_LDA(At, 1, 1); PG8_STAGE(PG8_SB(1, 0), b3, voffB); PG8_STAGE(PG8_SB(1, 1), b3 + hstep, voffB); PG8_STAGE(PG8_SA(1, 0), a3, voffA);
;             PG8_WAIT_V(8); PG8_WAIT_L(0); PG8_BAR; PG8_MMA(1, 0, At, B0); PG8_MMA(1, 1, At, B1); PG8_BAR; PG8_SCHED;
	s_add_i32 s64, 0, 0x18000
	s_add_i32 s65, 0, 0x1c000
	v_add_u32_e32 v140, s64, v169
	v_add_u32_e32 v177, s65, v169
	ds_read_b128 v[128:131], v140
	ds_read_b128 v[132:135], v140 offset:1024
	ds_read_b128 v[136:139], v140 offset:2048
	ds_read_b128 v[140:143], v140 offset:3072
	ds_read_b128 v[160:163], v177
	ds_read_b128 v[178:181], v177 offset:1024
	ds_read_b128 v[182:185], v177 offset:2048
	ds_read_b128 v[186:189], v177 offset:3072
	s_add_u32 s40, s40, 0x40000
	s_addc_u32 s41, s41, 0
	s_mov_b32 m0, s45
	ds_read_b128 v[190:193], v175 offset:32768
	ds_read_b128 v[194:197], v175 offset:33792
	ds_read_b128 v[198:201], v175 offset:34816
	ds_read_b128 v[202:205], v175 offset:35840
	ds_read_b128 v[206:209], v175 offset:36864
	ds_read_b128 v[210:213], v175 offset:37888
	ds_read_b128 v[214:217], v175 offset:38912
	ds_read_b128 v[218:221], v175 offset:39936
	global_load_lds_dwordx4 v144, s[40:41]
	s_mov_b32 m0, s46
	s_nop 0
	global_load_lds_dwordx4 v148, s[40:41]
	s_waitcnt vmcnt(8)
	s_waitcnt lgkmcnt(0)
	s_barrier
	s_setprio 1
	s_waitcnt lgkmcnt(0)
	v_mfma_f32_16x16x32_bf16 v[124:127], v[128:131], v[190:193], v[124:127]
	v_mfma_f32_16x16x32_bf16 v[120:123], v[136:139], v[190:193], v[120:123]
	v_mfma_f32_16x16x32_bf16 v[108:111], v[128:131], v[198:201], v[108:111]
	v_mfma_f32_16x16x32_bf16 v[104:107], v[136:139], v[198:201], v[104:107]
	v_mfma_f32_16x16x32_bf16 v[92:95], v[128:131], v[206:209], v[92:95]
	v_mfma_f32_16x16x32_bf16 v[88:91], v[136:139], v[206:209], v[88:91]
	v_mfma_f32_16x16x32_bf16 v[76:79], v[128:131], v[214:217], v[76:79]
	v_mfma_f32_16x16x32_bf16 v[72:75], v[136:139], v[214:217], v[72:75]
	v_mfma_f32_16x16x32_bf16 v[124:127], v[132:135], v[194:197], v[124:127]
	v_mfma_f32_16x16x32_bf16 v[120:123], v[140:143], v[194:197], v[120:123]
	v_mfma_f32_16x16x32_bf16 v[108:111], v[132:135], v[202:205], v[108:111]
	v_mfma_f32_16x16x32_bf16 v[104:107], v[140:143], v[202:205], v[104:107]
	v_mfma_f32_16x16x32_bf16 v[92:95], v[132:135], v[210:213], v[92:95]
	v_mfma_f32_16x16x32_bf16 v[88:91], v[140:143], v[210:213], v[88:91]
	v_mfma_f32_16x16x32_bf16 v[76:79], v[132:135], v[218:221], v[76:79]
	v_mfma_f32_16x16x32_bf16 v[72:75], v[140:143], v[218:221], v[72:75]
	s_setprio 0
	s_setprio 1
	v_mfma_f32_16x16x32_bf16 v[116:119], v[160:163], v[190:193], v[116:119]
	v_mfma_f32_16x16x32_bf16 v[112:115], v[182:185], v[190:193], v[112:115]
	v_mfma_f32_16x16x32_bf16 v[100:103], v[160:163], v[198:201], v[100:103]
	v_mfma_f32_16x16x32_bf16 v[96:99], v[182:185], v[198:201], v[96:99]
	v_mfma_f32_16x16x32_bf16 v[84:87], v[160:163], v[206:209], v[84:87]
	v_mfma_f32_16x16x32_bf16 v[80:83], v[182:185], v[206:209], v[80:83]
	v_mfma_f32_16x16x32_bf16 v[68:71], v[160:163], v[214:217], v[68:71]
	v_mfma_f32_16x16x32_bf16 v[64:67], v[182:185], v[214:217], v[64:67]
	v_mfma_f32_16x16x32_bf16 v[116:119], v[178:181], v[194:197], v[116:119]
	v_mfma_f32_16x16x32_bf16 v[112:115], v[186:189], v[194:197], v[112:115]
	v_mfma_f32_16x16x32_bf16 v[100:103], v[178:181], v[202:205], v[100:103]
	v_mfma_f32_16x16x32_bf16 v[96:99], v[186:189], v[202:205], v[96:99]
	v_mfma_f32_16x16x32_bf16 v[84:87], v[178:181], v[210:213], v[84:87]
	v_mfma_f32_16x16x32_bf16 v[80:83], v[186:189], v[210:213], v[80:83]
	v_mfma_f32_16x16x32_bf16 v[68:71], v[178:181], v[218:221], v[68:71]
	v_mfma_f32_16x16x32_bf16 v[64:67], v[186:189], v[218:221], v[64:67]
	s_setprio 0
	s_barrier
	s_add_u32 s98, s40, 0xfffc0080
	s_addc_u32 s99, s41, -1
	s_add_u32 s100, s38, 0x80
	s_addc_u32 s101, s39, 0
	s_add_i32 s40, s64, s30
	s_mov_b32 m0, s40
	ds_read_b128 v[190:193], v175 offset:49152
	ds_read_b128 v[194:197], v175 offset:50176
	ds_read_b128 v[198:201], v175 offset:51200
	ds_read_b128 v[202:205], v175 offset:52224
	ds_read_b128 v[206:209], v175 offset:53248
	ds_read_b128 v[210:213], v175 offset:54272
	ds_read_b128 v[214:217], v175 offset:55296
	ds_read_b128 v[218:221], v175 offset:56320
	global_load_lds_dwordx4 v146, s[100:101]
	s_add_i32 m0, s40, 0x2000
	s_add_u32 s38, s38, 0x40080
	s_addc_u32 s39, s39, 0
	s_add_i32 s40, s65, s30
	global_load_lds_dwordx4 v150, s[100:101]
	s_mov_b32 m0, s40
	s_nop 0
	global_load_lds_dwordx4 v146, s[38:39]
	s_add_i32 m0, s40, 0x2000
	s_nop 0
	global_load_lds_dwordx4 v150, s[38:39]
	s_mov_b32 m0, s47
	s_nop 0
	global_load_lds_dwordx4 v144, s[98:99]
	s_mov_b32 m0, s48
	s_nop 0
	global_load_lds_dwordx4 v148, s[98:99]
	s_waitcnt vmcnt(8)
	s_waitcnt lgkmcnt(0)
	s_barrier
	s_setprio 1
	s_waitcnt lgkmcnt(0)
	v_mfma_f32_16x16x32_bf16 v[60:63], v[128:131], v[190:193], v[60:63]
	v_mfma_f32_16x16x32_bf16 v[56:59], v[136:139], v[190:193], v[56:59]
	v_mfma_f32_16x16x32_bf16 v[44:47], v[128:131], v[198:201], v[44:47]
	v_mfma_f32_16x16x32_bf16 v[40:43], v[136:139], v[198:201], v[40:43]
	v_mfma_f32_16x16x32_bf16 v[28:31], v[128:131], v[206:209], v[28:31]
	v_mfma_f32_16x16x32_bf16 v[24:27], v[136:139], v[206:209], v[24:27]
	v_mfma_f32_16x16x32_bf16 v[12:15], v[128:131], v[214:217], v[12:15]
	v_mfma_f32_16x16x32_bf16 v[8:11], v[136:139], v[214:217], v[8:11]
	v_mfma_f32_16x16x32_bf16 v[60:63], v[132:135], v[194:197], v[60:63]
	v_mfma_f32_16x16x32_bf16 v[56:59], v[140:143], v[194:197], v[56:59]
	v_mfma_f32_16x16x32_bf16 v[44:47], v[132:135], v[202:205], v[44:47]
	v_mfma_f32_16x16x32_bf16 v[40:43], v[140:143], v[202:205], v[40:43]
	v_mfma_f32_16x16x32_bf16 v[28:31], v[132:135], v[210:213], v[28:31]
	v_mfma_f32_16x16x32_bf16 v[24:27], v[140:143], v[210:213], v[24:27]
	v_mfma_f32_16x16x32_bf16 v[12:15], v[132:135], v[218:221], v[12:15]
	v_mfma_f32_16x16x32_bf16 v[8:11], v[140:143], v[218:221], v[8:11]
	s_setprio 0
	s_setprio 1
	v_mfma_f32_16x16x32_bf16 v[52:55], v[160:163], v[190:193], v[52:55]
	v_mfma_f32_16x16x32_bf16 v[48:51], v[182:185], v[190:193], v[48:51]
	v_mfma_f32_16x16x32_bf16 v[36:39], v[160:163], v[198:201], v[36:39]
	v_mfma_f32_16x16x32_bf16 v[32:35], v[182:185], v[198:201], v[32:35]
	v_mfma_f32_16x16x32_bf16 v[20:23], v[160:163], v[206:209], v[20:23]
	v_mfma_f32_16x16x32_bf16 v[16:19], v[182:185], v[206:209], v[16:19]
	v_mfma_f32_16x16x32_bf16 v[4:7], v[160:163], v[214:217], v[4:7]
	v_mfma_f32_16x16x32_bf16 v[0:3], v[182:185], v[214:217], v[0:3]
	v_mfma_f32_16x16x32_bf16 v[52:55], v[178:181], v[194:197], v[52:55]
	v_mfma_f32_16x16x32_bf16 v[48:51], v[186:189], v[194:197], v[48:51]
	v_mfma_f32_16x16x32_bf16 v[36:39], v[178:181], v[202:205], v[36:39]
	v_mfma_f32_16x16x32_bf16 v[32:35], v[186:189], v[202:205], v[32:35]
	v_mfma_f32_16x16x32_bf16 v[20:23], v[178:181], v[210:213], v[20:23]
	v_mfma_f32_16x16x32_bf16 v[16:19], v[186:189], v[210:213], v[16:19]
	v_mfma_f32_16x16x32_bf16 v[4:7], v[178:181], v[218:221], v[4:7]
	v_mfma_f32_16x16x32_bf16 v[0:3], v[186:189], v[218:221], v[0:3]
	s_setprio 0
	s_barrier
	s_add_i32 s63, s63, 2
	s_add_u32 s36, s36, 0x100
	s_addc_u32 s37, s37, 0
	s_add_u32 s61, s61, 0x100
	s_addc_u32 s62, s62, 0
	s_cmp_gt_u32 s63, 13
	s_cbranch_scc0 .LBB0_755
	s_and_b64 vcc, exec, s[12:13]
	s_cbranch_vccz .LBB0_758
	s_barrier

; #define PG8_STAGE(bufoff, gbase, voff) do { _Pragma("unroll") for (int _i = 0; _i < 2; ++_i) \
;         __builtin_amdgcn_global_load_lds((const unsigned*)((const char*)(gbase) + (voff)[_i]), (PG8_LAS unsigned*)(lds + (bufoff) + ldsw + _i * 8192), 16, 0, 0); } while (0)
; #define PG8_LDA(dst, b, h) do { _Pragma("unroll") for (int m = 0; m < 4; ++m) _Pragma("unroll") for (int k = 0; k < 2; ++k) dst[m][k] = *(const PG8_LAS bf16x8*)(lds + PG8_SA(b, h) + aoff + m * 2048 + k * 1024); } while (0)
; #define PG8_LDB(dst, b, h) do { _Pragma("unroll") for (int n = 0; n < 2; ++n) _Pragma("unroll") for (int k = 0; k < 2; ++k) dst[n][k] = *(const PG8_LAS bf16x8*)(lds + PG8_SB(b, h) + boff + n * 2048 + k * 1024); } while (0)
; #define PG8_MMA(ai, bj, At, Bt) do { __builtin_amdgcn_s_setprio(1); _Pragma("unroll") for (int m = 0; m < 4; ++m) _Pragma("unroll") for (int n = 0; n < 2; ++n) _Pragma("unroll") for (int k = 0; k < 2; ++k) \
;         acc[ai][bj][m][n] = __builtin_amdgcn_mfma_f32_16x16x32_bf16(Bt[n][k], At[m][k], acc[ai][bj][m][n], 0, 0, 0); __builtin_amdgcn_s_setprio(0); } while (0)
; #define PG8_WAIT_V(n) asm volatile("s_waitcnt vmcnt(" #n ")" ::: "memory")
; #define PG8_WAIT_L(n) asm volatile("s_waitcnt lgkmcnt(" #n ")" ::: "memory")
; #define PG8_BAR __builtin_amdgcn_s_barrier()
; #define PG8_SCHED __builtin_amdgcn_sched_barrier(0)
; template <class Epi, class Sched, bool ALIGN_EPI = false, bool SP2 = false>
; __device__ __forceinline__ void gemm_phase(PG8_LAS unsigned char* lds, const Gemm g, const Sched& S, const Epi& E) {
;     ...
;             PG8_LDB(B0, 0, 0); PG8_LDB(B1, 0, 1); PG8_SCHED; PG8_LDA(At, 0, 0); PG8_STAGE(PG8_SA(1, 1), a1 + hstep, voffA);
;             PG8_WAIT_V(8); PG8_WAIT_L(0); PG8_BAR; PG8_MMA(0, 0, At, B0); PG8_MMA(0, 1, At, B1); PG8_BAR; PG8_SCHED;
;             PG8_LDA(At, 0, 1); PG8_STAGE(PG8_SB(0, 0), b2, voffB); PG8_STAGE(PG8_SB(0, 1), b2 + hstep, voffB); PG8_STAGE(PG8_SA(0, 0), a2, voffA);
;             PG8_WAIT_V(8); PG8_WAIT_L(0); PG8_BAR; PG8_MMA(1, 0, At, B0); PG8_MMA(1, 1, At, B1); PG8_BAR; PG8_SCHED;
.LBB0_842:
	ds_read_b128 v[144:147], v151
	ds_read_b128 v[156:159], v151 offset:1024
	ds_read_b128 v[160:163], v151 offset:2048
	ds_read_b128 v[168:171], v151 offset:3072
	ds_read_b128 v[172:175], v152
	ds_read_b128 v[176:179], v152 offset:1024
	ds_read_b128 v[180:183], v152 offset:2048
	ds_read_b128 v[184:187], v152 offset:3072
	s_add_u32 s26, s24, 0xfff00080
	s_addc_u32 s27, s25, -1
	s_cmp_eq_u32 s50, 60
	s_cselect_b32 s29, s17, s27
	s_cselect_b32 s28, s23, s26
	s_cselect_b32 s27, s15, s49
	s_cselect_b32 s26, s47, s48
	s_add_i32 m0, s34, 0xc000
	ds_read_b128 v[188:191], v153
	ds_read_b128 v[192:195], v153 offset:1024
	ds_read_b128 v[196:199], v153 offset:2048
	ds_read_b128 v[200:203], v153 offset:3072
	ds_read_b128 v[204:207], v153 offset:4096
	ds_read_b128 v[208:211], v153 offset:5120
	ds_read_b128 v[212:215], v153 offset:6144
	ds_read_b128 v[216:219], v153 offset:7168
	global_load_lds_dwordx4 v136, s[24:25]
	s_add_i32 m0, s34, 0xe000
	s_nop 0
	global_load_lds_dwordx4 v138, s[24:25]
	s_waitcnt vmcnt(8)
	s_waitcnt lgkmcnt(0)
	s_barrier
	s_setprio 1
	s_waitcnt lgkmcnt(0)
	v_mfma_f32_16x16x32_bf16 v[124:127], v[144:147], v[188:191], v[124:127]
	v_mfma_f32_16x16x32_bf16 v[120:123], v[160:163], v[188:191], v[120:123]
	v_mfma_f32_16x16x32_bf16 v[108:111], v[144:147], v[196:199], v[108:111]
	v_mfma_f32_16x16x32_bf16 v[104:107], v[160:163], v[196:199], v[104:107]
	v_mfma_f32_16x16x32_bf16 v[92:95], v[144:147], v[204:207], v[92:95]
	v_mfma_f32_16x16x32_bf16 v[88:91], v[160:163], v[204:207], v[88:91]
	v_mfma_f32_16x16x32_bf16 v[76:79], v[144:147], v[212:215], v[76:79]
	v_mfma_f32_16x16x32_bf16 v[72:75], v[160:163], v[212:215], v[72:75]
	v_mfma_f32_16x16x32_bf16 v[124:127], v[156:159], v[192:195], v[124:127]
	v_mfma_f32_16x16x32_bf16 v[120:123], v[168:171], v[192:195], v[120:123]
	v_mfma_f32_16x16x32_bf16 v[108:111], v[156:159], v[200:203], v[108:111]
	v_mfma_f32_16x16x32_bf16 v[104:107], v[168:171], v[200:203], v[104:107]
	v_mfma_f32_16x16x32_bf16 v[92:95], v[156:159], v[208:211], v[92:95]
	v_mfma_f32_16x16x32_bf16 v[88:91], v[168:171], v[208:211], v[88:91]
	v_mfma_f32_16x16x32_bf16 v[76:79], v[156:159], v[216:219], v[76:79]
	v_mfma_f32_16x16x32_bf16 v[72:75], v[168:171], v[216:219], v[72:75]
	s_setprio 0
	s_setprio 1
	v_mfma_f32_16x16x32_bf16 v[116:119], v[172:175], v[188:191], v[116:119]
	v_mfma_f32_16x16x32_bf16 v[112:115], v[180:183], v[188:191], v[112:115]
	v_mfma_f32_16x16x32_bf16 v[100:103], v[172:175], v[196:199], v[100:103]
	v_mfma_f32_16x16x32_bf16 v[96:99], v[180:183], v[196:199], v[96:99]
	v_mfma_f32_16x16x32_bf16 v[84:87], v[172:175], v[204:207], v[84:87]
	v_mfma_f32_16x16x32_bf16 v[80:83], v[180:183], v[204:207], v[80:83]
	v_mfma_f32_16x16x32_bf16 v[68:71], v[172:175], v[212:215], v[68:71]
	v_mfma_f32_16x16x32_bf16 v[64:67], v[180:183], v[212:215], v[64:67]
	v_mfma_f32_16x16x32_bf16 v[116:119], v[176:179], v[192:195], v[116:119]
	v_mfma_f32_16x16x32_bf16 v[112:115], v[184:187], v[192:195], v[112:115]
	v_mfma_f32_16x16x32_bf16 v[100:103], v[176:179], v[200:203], v[100:103]
	v_mfma_f32_16x16x32_bf16 v[96:99], v[184:187], v[200:203], v[96:99]
	v_mfma_f32_16x16x32_bf16 v[84:87], v[176:179], v[208:211], v[84:87]
	v_mfma_f32_16x16x32_bf16 v[80:83], v[184:187], v[208:211], v[80:83]
	v_mfma_f32_16x16x32_bf16 v[68:71], v[176:179], v[216:219], v[68:71]
	v_mfma_f32_16x16x32_bf16 v[64:67], v[184:187], v[216:219], v[64:67]
	s_setprio 0
	s_barrier
	s_add_i32 s51, s44, s33
	s_mov_b32 m0, s51
	ds_read_b128 v[188:191], v153 offset:16384
	ds_read_b128 v[192:195], v153 offset:17408
	ds_read_b128 v[196:199], v153 offset:18432
	ds_read_b128 v[200:203], v153 offset:19456
	ds_read_b128 v[204:207], v153 offset:20480
	ds_read_b128 v[208:211], v153 offset:21504
	ds_read_b128 v[212:215], v153 offset:22528
	ds_read_b128 v[216:219], v153 offset:23552
	global_load_lds_dwordx4 v130, s[26:27]
	s_add_i32 m0, s51, 0x2000
	s_add_u32 s52, s26, 0x100000
	s_addc_u32 s53, s27, 0
	s_add_i32 s51, s45, s33
	global_load_lds_dwordx4 v134, s[26:27]
	s_mov_b32 m0, s51
	s_nop 0
	global_load_lds_dwordx4 v130, s[52:53]
	s_add_i32 m0, s51, 0x2000
	s_nop 0
	global_load_lds_dwordx4 v134, s[52:53]
	s_mov_b32 m0, s34
	s_nop 0
	global_load_lds_dwordx4 v128, s[28:29]
	s_mov_b32 m0, s35
	s_nop 0
	global_load_lds_dwordx4 v132, s[28:29]
	s_waitcnt vmcnt(8)
	s_waitcnt lgkmcnt(0)
	s_barrier
	s_setprio 1
	s_waitcnt lgkmcnt(0)
	v_mfma_f32_16x16x32_bf16 v[60:63], v[144:147], v[188:191], v[60:63]
	v_mfma_f32_16x16x32_bf16 v[56:59], v[160:163], v[188:191], v[56:59]
	v_mfma_f32_16x16x32_bf16 v[44:47], v[144:147], v[196:199], v[44:47]
	v_mfma_f32_16x16x32_bf16 v[40:43], v[160:163], v[196:199], v[40:43]
	v_mfma_f32_16x16x32_bf16 v[28:31], v[144:147], v[204:207], v[28:31]
	v_mfma_f32_16x16x32_bf16 v[24:27], v[160:163], v[204:207], v[24:27]
	v_mfma_f32_16x16x32_bf16 v[12:15], v[144:147], v[212:215], v[12:15]
	v_mfma_f32_16x16x32_bf16 v[8:11], v[160:163], v[212:215], v[8:11]
	v_mfma_f32_16x16x32_bf16 v[60:63], v[156:159], v[192:195], v[60:63]
	v_mfma_f32_16x16x32_bf16 v[56:59], v[168:171], v[192:195], v[56:59]
	v_mfma_f32_16x16x32_bf16 v[44:47], v[156:159], v[200:203], v[44:47]
	v_mfma_f32_16x16x32_bf16 v[40:43], v[168:171], v[200:203], v[40:43]
	v_mfma_f32_16x16x32_bf16 v[28:31], v[156:159], v[208:211], v[28:31]
	v_mfma_f32_16x16x32_bf16 v[24:27], v[168:171], v[208:211], v[24:27]
	v_mfma_f32_16x16x32_bf16 v[12:15], v[156:159], v[216:219], v[12:15]
	v_mfma_f32_16x16x32_bf16 v[8:11], v[168:171], v[216:219], v[8:11]
	s_setprio 0
	s_setprio 1
	v_mfma_f32_16x16x32_bf16 v[52:55], v[172:175], v[188:191], v[52:55]
	v_mfma_f32_16x16x32_bf16 v[48:51], v[180:183], v[188:191], v[48:51]
	v_mfma_f32_16x16x32_bf16 v[36:39], v[172:175], v[196:199], v[36:39]
	v_mfma_f32_16x16x32_bf16 v[32:35], v[180:183], v[196:199], v[32:35]
	v_mfma_f32_16x16x32_bf16 v[20:23], v[172:175], v[204:207], v[20:23]
	v_mfma_f32_16x16x32_bf16 v[16:19], v[180:183], v[204:207], v[16:19]
	v_mfma_f32_16x16x32_bf16 v[4:7], v[172:175], v[212:215], v[4:7]
	v_mfma_f32_16x16x32_bf16 v[0:3], v[180:183], v[212:215], v[0:3]
	v_mfma_f32_16x16x32_bf16 v[52:55], v[176:179], v[192:195], v[52:55]
	v_mfma_f32_16x16x32_bf16 v[48:51], v[184:187], v[192:195], v[48:51]
	v_mfma_f32_16x16x32_bf16 v[36:39], v[176:179], v[200:203], v[36:39]
	v_mfma_f32_16x16x32_bf16 v[32:35], v[184:187], v[200:203], v[32:35]
	v_mfma_f32_16x16x32_bf16 v[20:23], v[176:179], v[208:211], v[20:23]
	v_mfma_f32_16x16x32_bf16 v[16:19], v[184:187], v[208:211], v[16:19]
	v_mfma_f32_16x16x32_bf16 v[4:7], v[176:179], v[216:219], v[4:7]
	v_mfma_f32_16x16x32_bf16 v[0:3], v[184:187], v[216:219], v[0:3]
	s_setprio 0
	s_barrier
; #define PG8_STAGE(bufoff, gbase, voff) do { _Pragma("unroll") for (int _i = 0; _i < 2; ++_i) \
;         __builtin_amdgcn_global_load_lds((const unsigned*)((const char*)(gbase) + (voff)[_i]), (PG8_LAS unsigned*)(lds + (bufoff) + ldsw + _i * 8192), 16, 0, 0); } while (0)
; #define PG8_LDA(dst, b, h) do { _Pragma("unroll") for (int m = 0; m < 4; ++m) _Pragma("unroll") for (int k = 0; k < 2; ++k) dst[m][k] = *(const PG8_LAS bf16x8*)(lds + PG8_SA(b, h) + aoff + m * 2048 + k * 1024); } while (0)
; #define PG8_LDB(dst, b, h) do { _Pragma("unroll") for (int n = 0; n < 2; ++n) _Pragma("unroll") for (int k = 0; k < 2; ++k) dst[n][k] = *(const PG8_LAS bf16x8*)(lds + PG8_SB(b, h) + boff + n * 2048 + k * 1024); } while (0)
; #define PG8_MMA(ai, bj, At, Bt) do { __builtin_amdgcn_s_setprio(1); _Pragma("unroll") for (int m = 0; m < 4; ++m) _Pragma("unroll") for (int n = 0; n < 2; ++n) _Pragma("unroll") for (int k = 0; k < 2; ++k) \
;         acc[ai][bj][m][n] = __builtin_amdgcn_mfma_f32_16x16x32_bf16(Bt[n][k], At[m][k], acc[ai][bj][m][n], 0, 0, 0); __builtin_amdgcn_s_setprio(0); } while (0)
; #define PG8_WAIT_V(n) asm volatile("s_waitcnt vmcnt(" #n ")" ::: "memory")
; #define PG8_WAIT_L(n) asm volatile("s_waitcnt lgkmcnt(" #n ")" ::: "memory")
; #define PG8_BAR __builtin_amdgcn_s_barrier()
; #define PG8_SCHED __builtin_amdgcn_sched_barrier(0)
; template <class Epi, class Sched, bool ALIGN_EPI = false, bool SP2 = false>
; __device__ __forceinline__ void gemm_phase(PG8_LAS unsigned char* lds, const Gemm g, const Sched& S, const Epi& E) {
;     ...
;             PG8_LDB(B0, 1, 0); PG8_LDB(B1, 1, 1); PG8_SCHED; PG8_LDA(At, 1, 0); PG8_STAGE(PG8_SA(0, 1), a2 + hstep, voffA);
;             PG8_WAIT_V(8); PG8_WAIT_L(0); PG8_BAR; PG8_MMA(0, 0, At, B0); PG8_MMA(0, 1, At, B1); PG8_BAR; PG8_SCHED;
	s_add_i32 s51, 0, 0x18000
	v_add_u32_e32 v155, s51, v149
	s_add_i32 s52, 0, 0x1c000
	ds_read_b128 v[144:147], v155
	ds_read_b128 v[156:159], v155 offset:1024
	ds_read_b128 v[160:163], v155 offset:2048
	ds_read_b128 v[168:171], v155 offset:3072
	v_add_u32_e32 v155, s52, v149
	ds_read_b128 v[172:175], v155
	ds_read_b128 v[176:179], v155 offset:1024
	ds_read_b128 v[180:183], v155 offset:2048
	ds_read_b128 v[184:187], v155 offset:3072
	s_add_u32 s28, s28, 0x100000
	s_addc_u32 s29, s29, 0
	s_mov_b32 m0, s36
	ds_read_b128 v[188:191], v153 offset:32768
	ds_read_b128 v[192:195], v153 offset:33792
	ds_read_b128 v[196:199], v153 offset:34816
	ds_read_b128 v[200:203], v153 offset:35840
	ds_read_b128 v[204:207], v153 offset:36864
	ds_read_b128 v[208:211], v153 offset:37888
	ds_read_b128 v[212:215], v153 offset:38912
	ds_read_b128 v[216:219], v153 offset:39936
	global_load_lds_dwordx4 v128, s[28:29]
	s_mov_b32 m0, s37
	s_nop 0
	global_load_lds_dwordx4 v132, s[28:29]
	s_waitcnt vmcnt(8)
	s_waitcnt lgkmcnt(0)
	s_barrier
	s_setprio 1
	s_waitcnt lgkmcnt(0)
	v_mfma_f32_16x16x32_bf16 v[124:127], v[144:147], v[188:191], v[124:127]
	v_mfma_f32_16x16x32_bf16 v[120:123], v[160:163], v[188:191], v[120:123]
	v_mfma_f32_16x16x32_bf16 v[108:111], v[144:147], v[196:199], v[108:111]
	v_mfma_f32_16x16x32_bf16 v[104:107], v[160:163], v[196:199], v[104:107]
	v_mfma_f32_16x16x32_bf16 v[92:95], v[144:147], v[204:207], v[92:95]
	v_mfma_f32_16x16x32_bf16 v[88:91], v[160:163], v[204:207], v[88:91]
	v_mfma_f32_16x16x32_bf16 v[76:79], v[144:147], v[212:215], v[76:79]
	v_mfma_f32_16x16x32_bf16 v[72:75], v[160:163], v[212:215], v[72:75]
	v_mfma_f32_16x16x32_bf16 v[124:127], v[156:159], v[192:195], v[124:127]
	v_mfma_f32_16x16x32_bf16 v[120:123], v[168:171], v[192:195], v[120:123]
	v_mfma_f32_16x16x32_bf16 v[108:111], v[156:159], v[200:203], v[108:111]
	v_mfma_f32_16x16x32_bf16 v[104:107], v[168:171], v[200:203], v[104:107]
	v_mfma_f32_16x16x32_bf16 v[92:95], v[156:159], v[208:211], v[92:95]
	v_mfma_f32_16x16x32_bf16 v[88:91], v[168:171], v[208:211], v[88:91]
	v_mfma_f32_16x16x32_bf16 v[76:79], v[156:159], v[216:219], v[76:79]
	v_mfma_f32_16x16x32_bf16 v[72:75], v[168:171], v[216:219], v[72:75]
	s_setprio 0
	s_setprio 1
	v_mfma_f32_16x16x32_bf16 v[116:119], v[172:175], v[188:191], v[116:119]
	v_mfma_f32_16x16x32_bf16 v[112:115], v[180:183], v[188:191], v[112:115]
	v_mfma_f32_16x16x32_bf16 v[100:103], v[172:175], v[196:199], v[100:103]
	v_mfma_f32_16x16x32_bf16 v[96:99], v[180:183], v[196:199], v[96:99]
	v_mfma_f32_16x16x32_bf16 v[84:87], v[172:175], v[204:207], v[84:87]
	v_mfma_f32_16x16x32_bf16 v[80:83], v[180:183], v[204:207], v[80:83]
	v_mfma_f32_16x16x32_bf16 v[68:71], v[172:175], v[212:215], v[68:71]
	v_mfma_f32_16x16x32_bf16 v[64:67], v[180:183], v[212:215], v[64:67]
	v_mfma_f32_16x16x32_bf16 v[116:119], v[176:179], v[192:195], v[116:119]
	v_mfma_f32_16x16x32_bf16 v[112:115], v[184:187], v[192:195], v[112:115]
	v_mfma_f32_16x16x32_bf16 v[100:103], v[176:179], v[200:203], v[100:103]
	v_mfma_f32_16x16x32_bf16 v[96:99], v[184:187], v[200:203], v[96:99]
	v_mfma_f32_16x16x32_bf16 v[84:87], v[176:179], v[208:211], v[84:87]
	v_mfma_f32_16x16x32_bf16 v[80:83], v[184:187], v[208:211], v[80:83]
	v_mfma_f32_16x16x32_bf16 v[68:71], v[176:179], v[216:219], v[68:71]
	v_mfma_f32_16x16x32_bf16 v[64:67], v[184:187], v[216:219], v[64:67]
	s_setprio 0
	s_barrier
; #define PG8_STAGE(bufoff, gbase, voff) do { _Pragma("unroll") for (int _i = 0; _i < 2; ++_i) \
;         __builtin_amdgcn_global_load_lds((const unsigned*)((const char*)(gbase) + (voff)[_i]), (PG8_LAS unsigned*)(lds + (bufoff) + ldsw + _i * 8192), 16, 0, 0); } while (0)
; #define PG8_LDA(dst, b, h) do { _Pragma("unroll") for (int m = 0; m < 4; ++m) _Pragma("unroll") for (int k = 0; k < 2; ++k) dst[m][k] = *(const PG8_LAS bf16x8*)(lds + PG8_SA(b, h) + aoff + m * 2048 + k * 1024); } while (0)
; #define PG8_MMA(ai, bj, At, Bt) do { __builtin_amdgcn_s_setprio(1); _Pragma("unroll") for (int m = 0; m < 4; ++m) _Pragma("unroll") for (int n = 0; n < 2; ++n) _Pragma("unroll") for (int k = 0; k < 2; ++k) \
;         acc[ai][bj][m][n] = __builtin_amdgcn_mfma_f32_16x16x32_bf16(Bt[n][k], At[m][k], acc[ai][bj][m][n], 0, 0, 0); __builtin_amdgcn_s_setprio(0); } while (0)
; #define PG8_WAIT_V(n) asm volatile("s_waitcnt vmcnt(" #n ")" ::: "memory")
; #define PG8_WAIT_L(n) asm volatile("s_waitcnt lgkmcnt(" #n ")" ::: "memory")
; #define PG8_BAR __builtin_amdgcn_s_barrier()
; #define PG8_SCHED __builtin_amdgcn_sched_barrier(0)
; template <class Epi, class Sched, bool ALIGN_EPI = false, bool SP2 = false>
; __device__ __forceinline__ void gemm_phase(PG8_LAS unsigned char* lds, const Gemm g, const Sched& S, const Epi& E) {
;     ...
;         for (int t = 0; t < nt; t += 2) {
;             const bool last = (t == nt - 2);
;     ...
;             PG8_LDA(At, 1, 1); PG8_STAGE(PG8_SB(1, 0), b3, voffB); PG8_STAGE(PG8_SB(1, 1), b3 + hstep, voffB); PG8_STAGE(PG8_SA(1, 0), a3, voffA);
;             PG8_WAIT_V(8); PG8_WAIT_L(0); PG8_BAR; PG8_MMA(1, 0, At, B0); PG8_MMA(1, 1, At, B1); PG8_BAR; PG8_SCHED;
	s_add_u32 s98, s28, 0xfff00080
	s_addc_u32 s99, s29, -1
	s_add_u32 s100, s26, 0x80
	s_addc_u32 s101, s27, 0
	s_add_i32 s28, s51, s33
	s_mov_b32 m0, s28
	ds_read_b128 v[188:191], v153 offset:49152
	ds_read_b128 v[192:195], v153 offset:50176
	ds_read_b128 v[196:199], v153 offset:51200
	ds_read_b128 v[200:203], v153 offset:52224
	ds_read_b128 v[204:207], v153 offset:53248
	ds_read_b128 v[208:211], v153 offset:54272
	ds_read_b128 v[212:215], v153 offset:55296
	ds_read_b128 v[216:219], v153 offset:56320
	global_load_lds_dwordx4 v130, s[100:101]
	s_add_i32 m0, s28, 0x2000
	s_add_u32 s26, s26, 0x100080
	s_addc_u32 s27, s27, 0
	s_add_i32 s28, s52, s33
	global_load_lds_dwordx4 v134, s[100:101]
	s_mov_b32 m0, s28
	s_nop 0
	global_load_lds_dwordx4 v130, s[26:27]
	s_add_i32 m0, s28, 0x2000
	s_nop 0
	global_load_lds_dwordx4 v134, s[26:27]
	s_mov_b32 m0, s39
	s_nop 0
	global_load_lds_dwordx4 v128, s[98:99]
	s_mov_b32 m0, s40
	s_nop 0
	global_load_lds_dwordx4 v132, s[98:99]
	s_waitcnt vmcnt(8)
	s_waitcnt lgkmcnt(0)
	s_barrier
	s_setprio 1
	s_waitcnt lgkmcnt(0)
	v_mfma_f32_16x16x32_bf16 v[60:63], v[144:147], v[188:191], v[60:63]
	v_mfma_f32_16x16x32_bf16 v[56:59], v[160:163], v[188:191], v[56:59]
	v_mfma_f32_16x16x32_bf16 v[44:47], v[144:147], v[196:199], v[44:47]
	v_mfma_f32_16x16x32_bf16 v[40:43], v[160:163], v[196:199], v[40:43]
	v_mfma_f32_16x16x32_bf16 v[28:31], v[144:147], v[204:207], v[28:31]
	v_mfma_f32_16x16x32_bf16 v[24:27], v[160:163], v[204:207], v[24:27]
	v_mfma_f32_16x16x32_bf16 v[12:15], v[144:147], v[212:215], v[12:15]
	v_mfma_f32_16x16x32_bf16 v[8:11], v[160:163], v[212:215], v[8:11]
	v_mfma_f32_16x16x32_bf16 v[60:63], v[156:159], v[192:195], v[60:63]
	v_mfma_f32_16x16x32_bf16 v[56:59], v[168:171], v[192:195], v[56:59]
	v_mfma_f32_16x16x32_bf16 v[44:47], v[156:159], v[200:203], v[44:47]
	v_mfma_f32_16x16x32_bf16 v[40:43], v[168:171], v[200:203], v[40:43]
	v_mfma_f32_16x16x32_bf16 v[28:31], v[156:159], v[208:211], v[28:31]
	v_mfma_f32_16x16x32_bf16 v[24:27], v[168:171], v[208:211], v[24:27]
	v_mfma_f32_16x16x32_bf16 v[12:15], v[156:159], v[216:219], v[12:15]
	v_mfma_f32_16x16x32_bf16 v[8:11], v[168:171], v[216:219], v[8:11]
	s_setprio 0
	s_setprio 1
	v_mfma_f32_16x16x32_bf16 v[52:55], v[172:175], v[188:191], v[52:55]
	v_mfma_f32_16x16x32_bf16 v[48:51], v[180:183], v[188:191], v[48:51]
	v_mfma_f32_16x16x32_bf16 v[36:39], v[172:175], v[196:199], v[36:39]
	v_mfma_f32_16x16x32_bf16 v[32:35], v[180:183], v[196:199], v[32:35]
	v_mfma_f32_16x16x32_bf16 v[20:23], v[172:175], v[204:207], v[20:23]
	v_mfma_f32_16x16x32_bf16 v[16:19], v[180:183], v[204:207], v[16:19]
	v_mfma_f32_16x16x32_bf16 v[4:7], v[172:175], v[212:215], v[4:7]
	v_mfma_f32_16x16x32_bf16 v[0:3], v[180:183], v[212:215], v[0:3]
	v_mfma_f32_16x16x32_bf16 v[52:55], v[176:179], v[192:195], v[52:55]
	v_mfma_f32_16x16x32_bf16 v[48:51], v[184:187], v[192:195], v[48:51]
	v_mfma_f32_16x16x32_bf16 v[36:39], v[176:179], v[200:203], v[36:39]
	v_mfma_f32_16x16x32_bf16 v[32:35], v[184:187], v[200:203], v[32:35]
	v_mfma_f32_16x16x32_bf16 v[20:23], v[176:179], v[208:211], v[20:23]
	v_mfma_f32_16x16x32_bf16 v[16:19], v[184:187], v[208:211], v[16:19]
	v_mfma_f32_16x16x32_bf16 v[4:7], v[176:179], v[216:219], v[4:7]
	v_mfma_f32_16x16x32_bf16 v[0:3], v[184:187], v[216:219], v[0:3]
	s_setprio 0
	s_barrier
	s_add_i32 s50, s50, 2
	s_add_u32 s24, s24, 0x100
	s_addc_u32 s25, s25, 0
	s_add_u32 s48, s48, 0x100
	s_addc_u32 s49, s49, 0
	s_cmp_gt_u32 s50, 61
	s_cbranch_scc0 .LBB0_842
	v_mbcnt_lo_u32_b32 v234, -1, 0
	v_mbcnt_hi_u32_b32 v234, -1, v234
	v_bfe_u32 v234, v234, 3, 1
	v_sub_u32_e32 v231, 0, v234
	v_and_b32_e32 v230, 0xffff8010, v231
	v_and_b32_e32 v235, 0x7ff0, v231
	v_sub_u32_e32 v244, 0x8000, v235
	v_mov_b32_e32 v245, 0
	s_mov_b32 s98, 0xff00ff
	s_mov_b32 s99, 0xff00ff
	s_and_b64 vcc, exec, s[12:13]
	s_cbranch_vccz .LBB0_845
	s_barrier

; #define PG8_STAGE(bufoff, gbase, voff) do { _Pragma("unroll") for (int _i = 0; _i < 2; ++_i) \
;         __builtin_amdgcn_global_load_lds((const unsigned*)((const char*)(gbase) + (voff)[_i]), (PG8_LAS unsigned*)(lds + (bufoff) + ldsw + _i * 8192), 16, 0, 0); } while (0)
; #define PG8_LDA(dst, b, h) do { _Pragma("unroll") for (int m = 0; m < 4; ++m) _Pragma("unroll") for (int k = 0; k < 2; ++k) dst[m][k] = *(const PG8_LAS bf16x8*)(lds + PG8_SA(b, h) + aoff + m * 2048 + k * 1024); } while (0)
; #define PG8_LDB(dst, b, h) do { _Pragma("unroll") for (int n = 0; n < 2; ++n) _Pragma("unroll") for (int k = 0; k < 2; ++k) dst[n][k] = *(const PG8_LAS bf16x8*)(lds + PG8_SB(b, h) + boff + n * 2048 + k * 1024); } while (0)
; #define PG8_MMA(ai, bj, At, Bt) do { __builtin_amdgcn_s_setprio(1); _Pragma("unroll") for (int m = 0; m < 4; ++m) _Pragma("unroll") for (int n = 0; n < 2; ++n) _Pragma("unroll") for (int k = 0; k < 2; ++k) \
;         acc[ai][bj][m][n] = __builtin_amdgcn_mfma_f32_16x16x32_bf16(Bt[n][k], At[m][k], acc[ai][bj][m][n], 0, 0, 0); __builtin_amdgcn_s_setprio(0); } while (0)
; #define PG8_WAIT_V(n) asm volatile("s_waitcnt vmcnt(" #n ")" ::: "memory")
; #define PG8_WAIT_L(n) asm volatile("s_waitcnt lgkmcnt(" #n ")" ::: "memory")
; #define PG8_BAR __builtin_amdgcn_s_barrier()
; #define PG8_SCHED __builtin_amdgcn_sched_barrier(0)
; template <class Epi, class Sched, bool ALIGN_EPI = false, bool SP2 = false>
; __device__ __forceinline__ void gemm_phase(PG8_LAS unsigned char* lds, const Gemm g, const Sched& S, const Epi& E) {
;     ...
;             PG8_LDB(B0, 0, 0); PG8_LDB(B1, 0, 1); PG8_SCHED; PG8_LDA(At, 0, 0); PG8_STAGE(PG8_SA(1, 1), a1 + hstep, voffA);
;             PG8_WAIT_V(8); PG8_WAIT_L(0); PG8_BAR; PG8_MMA(0, 0, At, B0); PG8_MMA(0, 1, At, B1); PG8_BAR; PG8_SCHED;
;             PG8_LDA(At, 0, 1); PG8_STAGE(PG8_SB(0, 0), b2, voffB); PG8_STAGE(PG8_SB(0, 1), b2 + hstep, voffB); PG8_STAGE(PG8_SA(0, 0), a2, voffA);
;             PG8_WAIT_V(8); PG8_WAIT_L(0); PG8_BAR; PG8_MMA(1, 0, At, B0); PG8_MMA(1, 1, At, B1); PG8_BAR; PG8_SCHED;
.LBB0_931:
	ds_read_b128 v[128:131], v171
	ds_read_b128 v[132:135], v171 offset:1024
	ds_read_b128 v[136:139], v171 offset:2048
	ds_read_b128 v[140:143], v171 offset:3072
	ds_read_b128 v[160:163], v172
	ds_read_b128 v[176:179], v172 offset:1024
	ds_read_b128 v[180:183], v172 offset:2048
	ds_read_b128 v[184:187], v172 offset:3072
	s_add_u32 s28, s26, 0xfffc0080
	s_addc_u32 s29, s27, -1
	s_cmp_eq_u32 s54, 12
	s_cselect_b32 s31, s17, s29
	s_cselect_b32 s30, s50, s28
	s_cselect_b32 s29, s15, s53
	s_cselect_b32 s28, s51, s52
	s_add_i32 m0, s25, 0xc000
	ds_read_b128 v[188:191], v173
	ds_read_b128 v[192:195], v173 offset:1024
	ds_read_b128 v[196:199], v173 offset:2048
	ds_read_b128 v[200:203], v173 offset:3072
	ds_read_b128 v[204:207], v173 offset:4096
	ds_read_b128 v[208:211], v173 offset:5120
	ds_read_b128 v[212:215], v173 offset:6144
	ds_read_b128 v[216:219], v173 offset:7168
	global_load_lds_dwordx4 v152, s[26:27]
	s_add_i32 m0, s25, 0xe000
	s_nop 0
	global_load_lds_dwordx4 v154, s[26:27]
	s_waitcnt vmcnt(8)
	s_waitcnt lgkmcnt(0)
	s_barrier
	s_setprio 1
	s_waitcnt lgkmcnt(0)
	v_mfma_f32_16x16x32_bf16 v[124:127], v[128:131], v[188:191], v[124:127]
	v_mfma_f32_16x16x32_bf16 v[120:123], v[136:139], v[188:191], v[120:123]
	v_mfma_f32_16x16x32_bf16 v[116:119], v[128:131], v[196:199], v[116:119]
	v_mfma_f32_16x16x32_bf16 v[108:111], v[136:139], v[196:199], v[108:111]
	v_mfma_f32_16x16x32_bf16 v[96:99], v[128:131], v[204:207], v[96:99]
	v_mfma_f32_16x16x32_bf16 v[88:91], v[136:139], v[204:207], v[88:91]
	v_mfma_f32_16x16x32_bf16 v[84:87], v[128:131], v[212:215], v[84:87]
	v_mfma_f32_16x16x32_bf16 v[76:79], v[136:139], v[212:215], v[76:79]
	v_mfma_f32_16x16x32_bf16 v[124:127], v[132:135], v[192:195], v[124:127]
	v_mfma_f32_16x16x32_bf16 v[120:123], v[140:143], v[192:195], v[120:123]
	v_mfma_f32_16x16x32_bf16 v[116:119], v[132:135], v[200:203], v[116:119]
	v_mfma_f32_16x16x32_bf16 v[108:111], v[140:143], v[200:203], v[108:111]
	v_mfma_f32_16x16x32_bf16 v[96:99], v[132:135], v[208:211], v[96:99]
	v_mfma_f32_16x16x32_bf16 v[88:91], v[140:143], v[208:211], v[88:91]
	v_mfma_f32_16x16x32_bf16 v[84:87], v[132:135], v[216:219], v[84:87]
	v_mfma_f32_16x16x32_bf16 v[76:79], v[140:143], v[216:219], v[76:79]
	s_setprio 0
	s_setprio 1
	v_mfma_f32_16x16x32_bf16 v[112:115], v[160:163], v[188:191], v[112:115]
	v_mfma_f32_16x16x32_bf16 v[104:107], v[180:183], v[188:191], v[104:107]
	v_mfma_f32_16x16x32_bf16 v[100:103], v[160:163], v[196:199], v[100:103]
	v_mfma_f32_16x16x32_bf16 v[92:95], v[180:183], v[196:199], v[92:95]
	v_mfma_f32_16x16x32_bf16 v[80:83], v[160:163], v[204:207], v[80:83]
	v_mfma_f32_16x16x32_bf16 v[72:75], v[180:183], v[204:207], v[72:75]
	v_mfma_f32_16x16x32_bf16 v[68:71], v[160:163], v[212:215], v[68:71]
	v_mfma_f32_16x16x32_bf16 v[64:67], v[180:183], v[212:215], v[64:67]
	v_mfma_f32_16x16x32_bf16 v[112:115], v[176:179], v[192:195], v[112:115]
	v_mfma_f32_16x16x32_bf16 v[104:107], v[184:187], v[192:195], v[104:107]
	v_mfma_f32_16x16x32_bf16 v[100:103], v[176:179], v[200:203], v[100:103]
	v_mfma_f32_16x16x32_bf16 v[92:95], v[184:187], v[200:203], v[92:95]
	v_mfma_f32_16x16x32_bf16 v[80:83], v[176:179], v[208:211], v[80:83]
	v_mfma_f32_16x16x32_bf16 v[72:75], v[184:187], v[208:211], v[72:75]
	v_mfma_f32_16x16x32_bf16 v[68:71], v[176:179], v[216:219], v[68:71]
	v_mfma_f32_16x16x32_bf16 v[64:67], v[184:187], v[216:219], v[64:67]
	s_setprio 0
	s_barrier
	s_add_i32 s55, s44, s22
	s_mov_b32 m0, s55
	ds_read_b128 v[188:191], v173 offset:16384
	ds_read_b128 v[192:195], v173 offset:17408
	ds_read_b128 v[196:199], v173 offset:18432
	ds_read_b128 v[200:203], v173 offset:19456
	ds_read_b128 v[204:207], v173 offset:20480
	ds_read_b128 v[208:211], v173 offset:21504
	ds_read_b128 v[212:215], v173 offset:22528
	ds_read_b128 v[216:219], v173 offset:23552
	global_load_lds_dwordx4 v146, s[28:29]
	s_add_i32 m0, s55, 0x2000
	s_add_u32 s56, s28, 0x40000
	s_addc_u32 s57, s29, 0
	s_add_i32 s55, s45, s22
	global_load_lds_dwordx4 v150, s[28:29]
	s_mov_b32 m0, s55
	s_nop 0
	global_load_lds_dwordx4 v146, s[56:57]
	s_add_i32 m0, s55, 0x2000
	s_nop 0
	global_load_lds_dwordx4 v150, s[56:57]
	s_mov_b32 m0, s25
	s_nop 0
	global_load_lds_dwordx4 v144, s[30:31]
	s_mov_b32 m0, s36
	s_nop 0
	global_load_lds_dwordx4 v148, s[30:31]
	s_waitcnt vmcnt(8)
	s_waitcnt lgkmcnt(0)
	s_barrier
	s_setprio 1
	s_waitcnt lgkmcnt(0)
	v_mfma_f32_16x16x32_bf16 v[60:63], v[128:131], v[188:191], v[60:63]
	v_mfma_f32_16x16x32_bf16 v[56:59], v[136:139], v[188:191], v[56:59]
	v_mfma_f32_16x16x32_bf16 v[52:55], v[128:131], v[196:199], v[52:55]
	v_mfma_f32_16x16x32_bf16 v[44:47], v[136:139], v[196:199], v[44:47]
	v_mfma_f32_16x16x32_bf16 v[32:35], v[128:131], v[204:207], v[32:35]
	v_mfma_f32_16x16x32_bf16 v[24:27], v[136:139], v[204:207], v[24:27]
	v_mfma_f32_16x16x32_bf16 v[20:23], v[128:131], v[212:215], v[20:23]
	v_mfma_f32_16x16x32_bf16 v[12:15], v[136:139], v[212:215], v[12:15]
	v_mfma_f32_16x16x32_bf16 v[60:63], v[132:135], v[192:195], v[60:63]
	v_mfma_f32_16x16x32_bf16 v[56:59], v[140:143], v[192:195], v[56:59]
	v_mfma_f32_16x16x32_bf16 v[52:55], v[132:135], v[200:203], v[52:55]
	v_mfma_f32_16x16x32_bf16 v[44:47], v[140:143], v[200:203], v[44:47]
	v_mfma_f32_16x16x32_bf16 v[32:35], v[132:135], v[208:211], v[32:35]
	v_mfma_f32_16x16x32_bf16 v[24:27], v[140:143], v[208:211], v[24:27]
	v_mfma_f32_16x16x32_bf16 v[20:23], v[132:135], v[216:219], v[20:23]
	v_mfma_f32_16x16x32_bf16 v[12:15], v[140:143], v[216:219], v[12:15]
	s_setprio 0
	s_setprio 1
	v_mfma_f32_16x16x32_bf16 v[48:51], v[160:163], v[188:191], v[48:51]
	v_mfma_f32_16x16x32_bf16 v[40:43], v[180:183], v[188:191], v[40:43]
	v_mfma_f32_16x16x32_bf16 v[36:39], v[160:163], v[196:199], v[36:39]
	v_mfma_f32_16x16x32_bf16 v[28:31], v[180:183], v[196:199], v[28:31]
	v_mfma_f32_16x16x32_bf16 v[16:19], v[160:163], v[204:207], v[16:19]
	v_mfma_f32_16x16x32_bf16 v[8:11], v[180:183], v[204:207], v[8:11]
	v_mfma_f32_16x16x32_bf16 v[4:7], v[160:163], v[212:215], v[4:7]
	v_mfma_f32_16x16x32_bf16 v[0:3], v[180:183], v[212:215], v[0:3]
	v_mfma_f32_16x16x32_bf16 v[48:51], v[176:179], v[192:195], v[48:51]
	v_mfma_f32_16x16x32_bf16 v[40:43], v[184:187], v[192:195], v[40:43]
	v_mfma_f32_16x16x32_bf16 v[36:39], v[176:179], v[200:203], v[36:39]
	v_mfma_f32_16x16x32_bf16 v[28:31], v[184:187], v[200:203], v[28:31]
	v_mfma_f32_16x16x32_bf16 v[16:19], v[176:179], v[208:211], v[16:19]
	v_mfma_f32_16x16x32_bf16 v[8:11], v[184:187], v[208:211], v[8:11]
	v_mfma_f32_16x16x32_bf16 v[4:7], v[176:179], v[216:219], v[4:7]
	v_mfma_f32_16x16x32_bf16 v[0:3], v[184:187], v[216:219], v[0:3]
	s_setprio 0
	s_barrier
; #define PG8_STAGE(bufoff, gbase, voff) do { _Pragma("unroll") for (int _i = 0; _i < 2; ++_i) \
;         __builtin_amdgcn_global_load_lds((const unsigned*)((const char*)(gbase) + (voff)[_i]), (PG8_LAS unsigned*)(lds + (bufoff) + ldsw + _i * 8192), 16, 0, 0); } while (0)
; #define PG8_LDA(dst, b, h) do { _Pragma("unroll") for (int m = 0; m < 4; ++m) _Pragma("unroll") for (int k = 0; k < 2; ++k) dst[m][k] = *(const PG8_LAS bf16x8*)(lds + PG8_SA(b, h) + aoff + m * 2048 + k * 1024); } while (0)
; #define PG8_LDB(dst, b, h) do { _Pragma("unroll") for (int n = 0; n < 2; ++n) _Pragma("unroll") for (int k = 0; k < 2; ++k) dst[n][k] = *(const PG8_LAS bf16x8*)(lds + PG8_SB(b, h) + boff + n * 2048 + k * 1024); } while (0)
; #define PG8_MMA(ai, bj, At, Bt) do { __builtin_amdgcn_s_setprio(1); _Pragma("unroll") for (int m = 0; m < 4; ++m) _Pragma("unroll") for (int n = 0; n < 2; ++n) _Pragma("unroll") for (int k = 0; k < 2; ++k) \
;         acc[ai][bj][m][n] = __builtin_amdgcn_mfma_f32_16x16x32_bf16(Bt[n][k], At[m][k], acc[ai][bj][m][n], 0, 0, 0); __builtin_amdgcn_s_setprio(0); } while (0)
; #define PG8_WAIT_V(n) asm volatile("s_waitcnt vmcnt(" #n ")" ::: "memory")
; #define PG8_WAIT_L(n) asm volatile("s_waitcnt lgkmcnt(" #n ")" ::: "memory")
; #define PG8_BAR __builtin_amdgcn_s_barrier()
; #define PG8_SCHED __builtin_amdgcn_sched_barrier(0)
; template <class Epi, class Sched, bool ALIGN_EPI = false, bool SP2 = false>
; __device__ __forceinline__ void gemm_phase(PG8_LAS unsigned char* lds, const Gemm g, const Sched& S, const Epi& E) {
;     ...
;             PG8_LDB(B0, 1, 0); PG8_LDB(B1, 1, 1); PG8_SCHED; PG8_LDA(At, 1, 0); PG8_STAGE(PG8_SA(0, 1), a2 + hstep, voffA);
;             PG8_WAIT_V(8); PG8_WAIT_L(0); PG8_BAR; PG8_MMA(0, 0, At, B0); PG8_MMA(0, 1, At, B1); PG8_BAR; PG8_SCHED;
;             PG8_LDA(At, 1, 1); PG8_STAGE(PG8_SB(1, 0), b3, voffB); PG8_STAGE(PG8_SB(1, 1), b3 + hstep, voffB); PG8_STAGE(PG8_SA(1, 0), a3, voffA);
;             PG8_WAIT_V(8); PG8_WAIT_L(0); PG8_BAR; PG8_MMA(1, 0, At, B0); PG8_MMA(1, 1, At, B1); PG8_BAR; PG8_SCHED;
	s_add_i32 s55, 0, 0x18000
	s_add_i32 s56, 0, 0x1c000
	v_add_u32_e32 v140, s55, v167
	v_add_u32_e32 v175, s56, v167
	ds_read_b128 v[128:131], v140
	ds_read_b128 v[132:135], v140 offset:1024
	ds_read_b128 v[136:139], v140 offset:2048
	ds_read_b128 v[140:143], v140 offset:3072
	ds_read_b128 v[160:163], v175
	ds_read_b128 v[176:179], v175 offset:1024
	ds_read_b128 v[180:183], v175 offset:2048
	ds_read_b128 v[184:187], v175 offset:3072
	s_add_u32 s30, s30, 0x40000
	s_addc_u32 s31, s31, 0
	s_mov_b32 m0, s37
	ds_read_b128 v[188:191], v173 offset:32768
	ds_read_b128 v[192:195], v173 offset:33792
	ds_read_b128 v[196:199], v173 offset:34816
	ds_read_b128 v[200:203], v173 offset:35840
	ds_read_b128 v[204:207], v173 offset:36864
	ds_read_b128 v[208:211], v173 offset:37888
	ds_read_b128 v[212:215], v173 offset:38912
	ds_read_b128 v[216:219], v173 offset:39936
	global_load_lds_dwordx4 v144, s[30:31]
	s_mov_b32 m0, s38
	s_nop 0
	global_load_lds_dwordx4 v148, s[30:31]
	s_waitcnt vmcnt(8)
	s_waitcnt lgkmcnt(0)
	s_barrier
	s_setprio 1
	s_waitcnt lgkmcnt(0)
	v_mfma_f32_16x16x32_bf16 v[124:127], v[128:131], v[188:191], v[124:127]
	v_mfma_f32_16x16x32_bf16 v[120:123], v[136:139], v[188:191], v[120:123]
	v_mfma_f32_16x16x32_bf16 v[116:119], v[128:131], v[196:199], v[116:119]
	v_mfma_f32_16x16x32_bf16 v[108:111], v[136:139], v[196:199], v[108:111]
	v_mfma_f32_16x16x32_bf16 v[96:99], v[128:131], v[204:207], v[96:99]
	v_mfma_f32_16x16x32_bf16 v[88:91], v[136:139], v[204:207], v[88:91]
	v_mfma_f32_16x16x32_bf16 v[84:87], v[128:131], v[212:215], v[84:87]
	v_mfma_f32_16x16x32_bf16 v[76:79], v[136:139], v[212:215], v[76:79]
	v_mfma_f32_16x16x32_bf16 v[124:127], v[132:135], v[192:195], v[124:127]
	v_mfma_f32_16x16x32_bf16 v[120:123], v[140:143], v[192:195], v[120:123]
	v_mfma_f32_16x16x32_bf16 v[116:119], v[132:135], v[200:203], v[116:119]
	v_mfma_f32_16x16x32_bf16 v[108:111], v[140:143], v[200:203], v[108:111]
	v_mfma_f32_16x16x32_bf16 v[96:99], v[132:135], v[208:211], v[96:99]
	v_mfma_f32_16x16x32_bf16 v[88:91], v[140:143], v[208:211], v[88:91]
	v_mfma_f32_16x16x32_bf16 v[84:87], v[132:135], v[216:219], v[84:87]
	v_mfma_f32_16x16x32_bf16 v[76:79], v[140:143], v[216:219], v[76:79]
	s_setprio 0
	s_setprio 1
	v_mfma_f32_16x16x32_bf16 v[112:115], v[160:163], v[188:191], v[112:115]
	v_mfma_f32_16x16x32_bf16 v[104:107], v[180:183], v[188:191], v[104:107]
	v_mfma_f32_16x16x32_bf16 v[100:103], v[160:163], v[196:199], v[100:103]
	v_mfma_f32_16x16x32_bf16 v[92:95], v[180:183], v[196:199], v[92:95]
	v_mfma_f32_16x16x32_bf16 v[80:83], v[160:163], v[204:207], v[80:83]
	v_mfma_f32_16x16x32_bf16 v[72:75], v[180:183], v[204:207], v[72:75]
	v_mfma_f32_16x16x32_bf16 v[68:71], v[160:163], v[212:215], v[68:71]
	v_mfma_f32_16x16x32_bf16 v[64:67], v[180:183], v[212:215], v[64:67]
	v_mfma_f32_16x16x32_bf16 v[112:115], v[176:179], v[192:195], v[112:115]
	v_mfma_f32_16x16x32_bf16 v[104:107], v[184:187], v[192:195], v[104:107]
	v_mfma_f32_16x16x32_bf16 v[100:103], v[176:179], v[200:203], v[100:103]
	v_mfma_f32_16x16x32_bf16 v[92:95], v[184:187], v[200:203], v[92:95]
	v_mfma_f32_16x16x32_bf16 v[80:83], v[176:179], v[208:211], v[80:83]
	v_mfma_f32_16x16x32_bf16 v[72:75], v[184:187], v[208:211], v[72:75]
	v_mfma_f32_16x16x32_bf16 v[68:71], v[176:179], v[216:219], v[68:71]
	v_mfma_f32_16x16x32_bf16 v[64:67], v[184:187], v[216:219], v[64:67]
	s_setprio 0
	s_barrier
	s_add_u32 s98, s30, 0xfffc0080
	s_addc_u32 s99, s31, -1
	s_add_u32 s100, s28, 0x80
	s_addc_u32 s101, s29, 0
	s_add_i32 s30, s55, s22
	s_mov_b32 m0, s30
	ds_read_b128 v[188:191], v173 offset:49152
	ds_read_b128 v[192:195], v173 offset:50176
	ds_read_b128 v[196:199], v173 offset:51200
	ds_read_b128 v[200:203], v173 offset:52224
	ds_read_b128 v[204:207], v173 offset:53248
	ds_read_b128 v[208:211], v173 offset:54272
	ds_read_b128 v[212:215], v173 offset:55296
	ds_read_b128 v[216:219], v173 offset:56320
	global_load_lds_dwordx4 v146, s[100:101]
	s_add_i32 m0, s30, 0x2000
	s_add_u32 s28, s28, 0x40080
	s_addc_u32 s29, s29, 0
	s_add_i32 s30, s56, s22
	global_load_lds_dwordx4 v150, s[100:101]
	s_mov_b32 m0, s30
	s_nop 0
	global_load_lds_dwordx4 v146, s[28:29]
	s_add_i32 m0, s30, 0x2000
	s_nop 0
	global_load_lds_dwordx4 v150, s[28:29]
	s_mov_b32 m0, s39
	s_nop 0
	global_load_lds_dwordx4 v144, s[98:99]
	s_mov_b32 m0, s40
	s_nop 0
	global_load_lds_dwordx4 v148, s[98:99]
	s_waitcnt vmcnt(8)
	s_waitcnt lgkmcnt(0)
	s_barrier
	s_setprio 1
	s_waitcnt lgkmcnt(0)
	v_mfma_f32_16x16x32_bf16 v[60:63], v[128:131], v[188:191], v[60:63]
	v_mfma_f32_16x16x32_bf16 v[56:59], v[136:139], v[188:191], v[56:59]
	v_mfma_f32_16x16x32_bf16 v[52:55], v[128:131], v[196:199], v[52:55]
	v_mfma_f32_16x16x32_bf16 v[44:47], v[136:139], v[196:199], v[44:47]
	v_mfma_f32_16x16x32_bf16 v[32:35], v[128:131], v[204:207], v[32:35]
	v_mfma_f32_16x16x32_bf16 v[24:27], v[136:139], v[204:207], v[24:27]
	v_mfma_f32_16x16x32_bf16 v[20:23], v[128:131], v[212:215], v[20:23]
	v_mfma_f32_16x16x32_bf16 v[12:15], v[136:139], v[212:215], v[12:15]
	v_mfma_f32_16x16x32_bf16 v[60:63], v[132:135], v[192:195], v[60:63]
	v_mfma_f32_16x16x32_bf16 v[56:59], v[140:143], v[192:195], v[56:59]
	v_mfma_f32_16x16x32_bf16 v[52:55], v[132:135], v[200:203], v[52:55]
	v_mfma_f32_16x16x32_bf16 v[44:47], v[140:143], v[200:203], v[44:47]
	v_mfma_f32_16x16x32_bf16 v[32:35], v[132:135], v[208:211], v[32:35]
	v_mfma_f32_16x16x32_bf16 v[24:27], v[140:143], v[208:211], v[24:27]
	v_mfma_f32_16x16x32_bf16 v[20:23], v[132:135], v[216:219], v[20:23]
	v_mfma_f32_16x16x32_bf16 v[12:15], v[140:143], v[216:219], v[12:15]
	s_setprio 0
	s_setprio 1
	v_mfma_f32_16x16x32_bf16 v[48:51], v[160:163], v[188:191], v[48:51]
	v_mfma_f32_16x16x32_bf16 v[40:43], v[180:183], v[188:191], v[40:43]
	v_mfma_f32_16x16x32_bf16 v[36:39], v[160:163], v[196:199], v[36:39]
	v_mfma_f32_16x16x32_bf16 v[28:31], v[180:183], v[196:199], v[28:31]
	v_mfma_f32_16x16x32_bf16 v[16:19], v[160:163], v[204:207], v[16:19]
	v_mfma_f32_16x16x32_bf16 v[8:11], v[180:183], v[204:207], v[8:11]
	v_mfma_f32_16x16x32_bf16 v[4:7], v[160:163], v[212:215], v[4:7]
	v_mfma_f32_16x16x32_bf16 v[0:3], v[180:183], v[212:215], v[0:3]
	v_mfma_f32_16x16x32_bf16 v[48:51], v[176:179], v[192:195], v[48:51]
	v_mfma_f32_16x16x32_bf16 v[40:43], v[184:187], v[192:195], v[40:43]
	v_mfma_f32_16x16x32_bf16 v[36:39], v[176:179], v[200:203], v[36:39]
	v_mfma_f32_16x16x32_bf16 v[28:31], v[184:187], v[200:203], v[28:31]
	v_mfma_f32_16x16x32_bf16 v[16:19], v[176:179], v[208:211], v[16:19]
	v_mfma_f32_16x16x32_bf16 v[8:11], v[184:187], v[208:211], v[8:11]
	v_mfma_f32_16x16x32_bf16 v[4:7], v[176:179], v[216:219], v[4:7]
	v_mfma_f32_16x16x32_bf16 v[0:3], v[184:187], v[216:219], v[0:3]
	s_setprio 0
	s_barrier
	s_add_i32 s54, s54, 2
	s_add_u32 s26, s26, 0x100
	s_addc_u32 s27, s27, 0
	s_add_u32 s52, s52, 0x100
	s_addc_u32 s53, s53, 0
	s_cmp_gt_u32 s54, 13
	s_cbranch_scc0 .LBB0_931
	s_and_b64 vcc, exec, s[12:13]
	s_cbranch_vccz .LBB0_934
	s_barrier

; #define PG8_STAGE(bufoff, gbase, voff) do { _Pragma("unroll") for (int _i = 0; _i < 2; ++_i) \
;         __builtin_amdgcn_global_load_lds((const unsigned*)((const char*)(gbase) + (voff)[_i]), (PG8_LAS unsigned*)(lds + (bufoff) + ldsw + _i * 8192), 16, 0, 0); } while (0)
; #define PG8_LDA(dst, b, h) do { _Pragma("unroll") for (int m = 0; m < 4; ++m) _Pragma("unroll") for (int k = 0; k < 2; ++k) dst[m][k] = *(const PG8_LAS bf16x8*)(lds + PG8_SA(b, h) + aoff + m * 2048 + k * 1024); } while (0)
; #define PG8_LDB(dst, b, h) do { _Pragma("unroll") for (int n = 0; n < 2; ++n) _Pragma("unroll") for (int k = 0; k < 2; ++k) dst[n][k] = *(const PG8_LAS bf16x8*)(lds + PG8_SB(b, h) + boff + n * 2048 + k * 1024); } while (0)
; #define PG8_MMA(ai, bj, At, Bt) do { __builtin_amdgcn_s_setprio(1); _Pragma("unroll") for (int m = 0; m < 4; ++m) _Pragma("unroll") for (int n = 0; n < 2; ++n) _Pragma("unroll") for (int k = 0; k < 2; ++k) \
;         acc[ai][bj][m][n] = __builtin_amdgcn_mfma_f32_16x16x32_bf16(Bt[n][k], At[m][k], acc[ai][bj][m][n], 0, 0, 0); __builtin_amdgcn_s_setprio(0); } while (0)
; #define PG8_WAIT_V(n) asm volatile("s_waitcnt vmcnt(" #n ")" ::: "memory")
; #define PG8_WAIT_L(n) asm volatile("s_waitcnt lgkmcnt(" #n ")" ::: "memory")
; #define PG8_BAR __builtin_amdgcn_s_barrier()
; #define PG8_SCHED __builtin_amdgcn_sched_barrier(0)
; template <class Epi, class Sched, bool ALIGN_EPI = false, bool SP2 = false>
; __device__ __forceinline__ void gemm_phase(PG8_LAS unsigned char* lds, const Gemm g, const Sched& S, const Epi& E) {
;     ...
;             PG8_LDB(B0, 0, 0); PG8_LDB(B1, 0, 1); PG8_SCHED; PG8_LDA(At, 0, 0); PG8_STAGE(PG8_SA(1, 1), a1 + hstep, voffA);
;             PG8_WAIT_V(8); PG8_WAIT_L(0); PG8_BAR; PG8_MMA(0, 0, At, B0); PG8_MMA(0, 1, At, B1); PG8_BAR; PG8_SCHED;
;             PG8_LDA(At, 0, 1); PG8_STAGE(PG8_SB(0, 0), b2, voffB); PG8_STAGE(PG8_SB(0, 1), b2 + hstep, voffB); PG8_STAGE(PG8_SA(0, 0), a2, voffA);
;             PG8_WAIT_V(8); PG8_WAIT_L(0); PG8_BAR; PG8_MMA(1, 0, At, B0); PG8_MMA(1, 1, At, B1); PG8_BAR; PG8_SCHED;
.LBB0_1556:
	ds_read_b128 v[128:131], v173
	ds_read_b128 v[132:135], v173 offset:1024
	ds_read_b128 v[136:139], v173 offset:2048
	ds_read_b128 v[140:143], v173 offset:3072
	ds_read_b128 v[160:163], v174
	ds_read_b128 v[178:181], v174 offset:1024
	ds_read_b128 v[182:185], v174 offset:2048
	ds_read_b128 v[186:189], v174 offset:3072
	s_add_u32 s38, s36, 0xfffc0080
	s_addc_u32 s39, s37, -1
	s_cmp_eq_u32 s64, 12
	s_cselect_b32 s41, s25, s39
	s_cselect_b32 s40, s60, s38
	s_cselect_b32 s39, s23, s63
	s_cselect_b32 s38, s61, s62
	s_add_i32 m0, s35, 0xc000
	ds_read_b128 v[190:193], v175
	ds_read_b128 v[194:197], v175 offset:1024
	ds_read_b128 v[198:201], v175 offset:2048
	ds_read_b128 v[202:205], v175 offset:3072
	ds_read_b128 v[206:209], v175 offset:4096
	ds_read_b128 v[210:213], v175 offset:5120
	ds_read_b128 v[214:217], v175 offset:6144
	ds_read_b128 v[218:221], v175 offset:7168
	global_load_lds_dwordx4 v152, s[36:37]
	s_add_i32 m0, s35, 0xe000
	s_nop 0
	global_load_lds_dwordx4 v154, s[36:37]
	s_waitcnt vmcnt(8)
	s_waitcnt lgkmcnt(0)
	s_barrier
	s_setprio 1
	s_waitcnt lgkmcnt(0)
	v_mfma_f32_16x16x32_bf16 v[124:127], v[128:131], v[190:193], v[124:127]
	v_mfma_f32_16x16x32_bf16 v[120:123], v[136:139], v[190:193], v[120:123]
	v_mfma_f32_16x16x32_bf16 v[108:111], v[128:131], v[198:201], v[108:111]
	v_mfma_f32_16x16x32_bf16 v[104:107], v[136:139], v[198:201], v[104:107]
	v_mfma_f32_16x16x32_bf16 v[92:95], v[128:131], v[206:209], v[92:95]
	v_mfma_f32_16x16x32_bf16 v[88:91], v[136:139], v[206:209], v[88:91]
	v_mfma_f32_16x16x32_bf16 v[76:79], v[128:131], v[214:217], v[76:79]
	v_mfma_f32_16x16x32_bf16 v[72:75], v[136:139], v[214:217], v[72:75]
	v_mfma_f32_16x16x32_bf16 v[124:127], v[132:135], v[194:197], v[124:127]
	v_mfma_f32_16x16x32_bf16 v[120:123], v[140:143], v[194:197], v[120:123]
	v_mfma_f32_16x16x32_bf16 v[108:111], v[132:135], v[202:205], v[108:111]
	v_mfma_f32_16x16x32_bf16 v[104:107], v[140:143], v[202:205], v[104:107]
	v_mfma_f32_16x16x32_bf16 v[92:95], v[132:135], v[210:213], v[92:95]
	v_mfma_f32_16x16x32_bf16 v[88:91], v[140:143], v[210:213], v[88:91]
	v_mfma_f32_16x16x32_bf16 v[76:79], v[132:135], v[218:221], v[76:79]
	v_mfma_f32_16x16x32_bf16 v[72:75], v[140:143], v[218:221], v[72:75]
	s_setprio 0
	s_setprio 1
	v_mfma_f32_16x16x32_bf16 v[116:119], v[160:163], v[190:193], v[116:119]
	v_mfma_f32_16x16x32_bf16 v[112:115], v[182:185], v[190:193], v[112:115]
	v_mfma_f32_16x16x32_bf16 v[100:103], v[160:163], v[198:201], v[100:103]
	v_mfma_f32_16x16x32_bf16 v[96:99], v[182:185], v[198:201], v[96:99]
	v_mfma_f32_16x16x32_bf16 v[84:87], v[160:163], v[206:209], v[84:87]
	v_mfma_f32_16x16x32_bf16 v[80:83], v[182:185], v[206:209], v[80:83]
	v_mfma_f32_16x16x32_bf16 v[68:71], v[160:163], v[214:217], v[68:71]
	v_mfma_f32_16x16x32_bf16 v[64:67], v[182:185], v[214:217], v[64:67]
	v_mfma_f32_16x16x32_bf16 v[116:119], v[178:181], v[194:197], v[116:119]
	v_mfma_f32_16x16x32_bf16 v[112:115], v[186:189], v[194:197], v[112:115]
	v_mfma_f32_16x16x32_bf16 v[100:103], v[178:181], v[202:205], v[100:103]
	v_mfma_f32_16x16x32_bf16 v[96:99], v[186:189], v[202:205], v[96:99]
	v_mfma_f32_16x16x32_bf16 v[84:87], v[178:181], v[210:213], v[84:87]
	v_mfma_f32_16x16x32_bf16 v[80:83], v[186:189], v[210:213], v[80:83]
	v_mfma_f32_16x16x32_bf16 v[68:71], v[178:181], v[218:221], v[68:71]
	v_mfma_f32_16x16x32_bf16 v[64:67], v[186:189], v[218:221], v[64:67]
	s_setprio 0
	s_barrier
	s_add_i32 s65, s51, s30
	s_mov_b32 m0, s65
	ds_read_b128 v[190:193], v175 offset:16384
	ds_read_b128 v[194:197], v175 offset:17408
	ds_read_b128 v[198:201], v175 offset:18432
	ds_read_b128 v[202:205], v175 offset:19456
	ds_read_b128 v[206:209], v175 offset:20480
	ds_read_b128 v[210:213], v175 offset:21504
	ds_read_b128 v[214:217], v175 offset:22528
	ds_read_b128 v[218:221], v175 offset:23552
	global_load_lds_dwordx4 v146, s[38:39]
	s_add_i32 m0, s65, 0x2000
	s_add_u32 s66, s38, 0x40000
	s_addc_u32 s67, s39, 0
	s_add_i32 s65, s52, s30
	global_load_lds_dwordx4 v150, s[38:39]
	s_mov_b32 m0, s65
	s_nop 0
	global_load_lds_dwordx4 v146, s[66:67]
	s_add_i32 m0, s65, 0x2000
	s_nop 0
	global_load_lds_dwordx4 v150, s[66:67]
	s_mov_b32 m0, s35
	s_nop 0
	global_load_lds_dwordx4 v144, s[40:41]
	s_mov_b32 m0, s44
	s_nop 0
	global_load_lds_dwordx4 v148, s[40:41]
	s_waitcnt vmcnt(8)
	s_waitcnt lgkmcnt(0)
	s_barrier
	s_setprio 1
	s_waitcnt lgkmcnt(0)
	v_mfma_f32_16x16x32_bf16 v[60:63], v[128:131], v[190:193], v[60:63]
	v_mfma_f32_16x16x32_bf16 v[56:59], v[136:139], v[190:193], v[56:59]
	v_mfma_f32_16x16x32_bf16 v[44:47], v[128:131], v[198:201], v[44:47]
	v_mfma_f32_16x16x32_bf16 v[40:43], v[136:139], v[198:201], v[40:43]
	v_mfma_f32_16x16x32_bf16 v[28:31], v[128:131], v[206:209], v[28:31]
	v_mfma_f32_16x16x32_bf16 v[24:27], v[136:139], v[206:209], v[24:27]
	v_mfma_f32_16x16x32_bf16 v[12:15], v[128:131], v[214:217], v[12:15]
	v_mfma_f32_16x16x32_bf16 v[8:11], v[136:139], v[214:217], v[8:11]
	v_mfma_f32_16x16x32_bf16 v[60:63], v[132:135], v[194:197], v[60:63]
	v_mfma_f32_16x16x32_bf16 v[56:59], v[140:143], v[194:197], v[56:59]
	v_mfma_f32_16x16x32_bf16 v[44:47], v[132:135], v[202:205], v[44:47]
	v_mfma_f32_16x16x32_bf16 v[40:43], v[140:143], v[202:205], v[40:43]
	v_mfma_f32_16x16x32_bf16 v[28:31], v[132:135], v[210:213], v[28:31]
	v_mfma_f32_16x16x32_bf16 v[24:27], v[140:143], v[210:213], v[24:27]
	v_mfma_f32_16x16x32_bf16 v[12:15], v[132:135], v[218:221], v[12:15]
	v_mfma_f32_16x16x32_bf16 v[8:11], v[140:143], v[218:221], v[8:11]
	s_setprio 0
	s_setprio 1
	v_mfma_f32_16x16x32_bf16 v[52:55], v[160:163], v[190:193], v[52:55]
	v_mfma_f32_16x16x32_bf16 v[48:51], v[182:185], v[190:193], v[48:51]
	v_mfma_f32_16x16x32_bf16 v[36:39], v[160:163], v[198:201], v[36:39]
	v_mfma_f32_16x16x32_bf16 v[32:35], v[182:185], v[198:201], v[32:35]
	v_mfma_f32_16x16x32_bf16 v[20:23], v[160:163], v[206:209], v[20:23]
	v_mfma_f32_16x16x32_bf16 v[16:19], v[182:185], v[206:209], v[16:19]
	v_mfma_f32_16x16x32_bf16 v[4:7], v[160:163], v[214:217], v[4:7]
	v_mfma_f32_16x16x32_bf16 v[0:3], v[182:185], v[214:217], v[0:3]
	v_mfma_f32_16x16x32_bf16 v[52:55], v[178:181], v[194:197], v[52:55]
	v_mfma_f32_16x16x32_bf16 v[48:51], v[186:189], v[194:197], v[48:51]
	v_mfma_f32_16x16x32_bf16 v[36:39], v[178:181], v[202:205], v[36:39]
	v_mfma_f32_16x16x32_bf16 v[32:35], v[186:189], v[202:205], v[32:35]
	v_mfma_f32_16x16x32_bf16 v[20:23], v[178:181], v[210:213], v[20:23]
	v_mfma_f32_16x16x32_bf16 v[16:19], v[186:189], v[210:213], v[16:19]
	v_mfma_f32_16x16x32_bf16 v[4:7], v[178:181], v[218:221], v[4:7]
	v_mfma_f32_16x16x32_bf16 v[0:3], v[186:189], v[218:221], v[0:3]
	s_setprio 0
	s_barrier
; #define PG8_STAGE(bufoff, gbase, voff) do { _Pragma("unroll") for (int _i = 0; _i < 2; ++_i) \
;         __builtin_amdgcn_global_load_lds((const unsigned*)((const char*)(gbase) + (voff)[_i]), (PG8_LAS unsigned*)(lds + (bufoff) + ldsw + _i * 8192), 16, 0, 0); } while (0)
; #define PG8_LDA(dst, b, h) do { _Pragma("unroll") for (int m = 0; m < 4; ++m) _Pragma("unroll") for (int k = 0; k < 2; ++k) dst[m][k] = *(const PG8_LAS bf16x8*)(lds + PG8_SA(b, h) + aoff + m * 2048 + k * 1024); } while (0)
; #define PG8_LDB(dst, b, h) do { _Pragma("unroll") for (int n = 0; n < 2; ++n) _Pragma("unroll") for (int k = 0; k < 2; ++k) dst[n][k] = *(const PG8_LAS bf16x8*)(lds + PG8_SB(b, h) + boff + n * 2048 + k * 1024); } while (0)
; #define PG8_MMA(ai, bj, At, Bt) do { __builtin_amdgcn_s_setprio(1); _Pragma("unroll") for (int m = 0; m < 4; ++m) _Pragma("unroll") for (int n = 0; n < 2; ++n) _Pragma("unroll") for (int k = 0; k < 2; ++k) \
;         acc[ai][bj][m][n] = __builtin_amdgcn_mfma_f32_16x16x32_bf16(Bt[n][k], At[m][k], acc[ai][bj][m][n], 0, 0, 0); __builtin_amdgcn_s_setprio(0); } while (0)
; #define PG8_WAIT_V(n) asm volatile("s_waitcnt vmcnt(" #n ")" ::: "memory")
; #define PG8_WAIT_L(n) asm volatile("s_waitcnt lgkmcnt(" #n ")" ::: "memory")
; #define PG8_BAR __builtin_amdgcn_s_barrier()
; #define PG8_SCHED __builtin_amdgcn_sched_barrier(0)
; template <class Epi, class Sched, bool ALIGN_EPI = false, bool SP2 = false>
; __device__ __forceinline__ void gemm_phase(PG8_LAS unsigned char* lds, const Gemm g, const Sched& S, const Epi& E) {
;     ...
;             PG8_LDB(B0, 1, 0); PG8_LDB(B1, 1, 1); PG8_SCHED; PG8_LDA(At, 1, 0); PG8_STAGE(PG8_SA(0, 1), a2 + hstep, voffA);
;             PG8_WAIT_V(8); PG8_WAIT_L(0); PG8_BAR; PG8_MMA(0, 0, At, B0); PG8_MMA(0, 1, At, B1); PG8_BAR; PG8_SCHED;
;             PG8_LDA(At, 1, 1); PG8_STAGE(PG8_SB(1, 0), b3, voffB); PG8_STAGE(PG8_SB(1, 1), b3 + hstep, voffB); PG8_STAGE(PG8_SA(1, 0), a3, voffA);
;             PG8_WAIT_V(8); PG8_WAIT_L(0); PG8_BAR; PG8_MMA(1, 0, At, B0); PG8_MMA(1, 1, At, B1); PG8_BAR; PG8_SCHED;
	s_add_i32 s65, 0, 0x18000
	s_add_i32 s66, 0, 0x1c000
	v_add_u32_e32 v140, s65, v169
	v_add_u32_e32 v177, s66, v169
	ds_read_b128 v[128:131], v140
	ds_read_b128 v[132:135], v140 offset:1024
	ds_read_b128 v[136:139], v140 offset:2048
	ds_read_b128 v[140:143], v140 offset:3072
	ds_read_b128 v[160:163], v177
	ds_read_b128 v[178:181], v177 offset:1024
	ds_read_b128 v[182:185], v177 offset:2048
	ds_read_b128 v[186:189], v177 offset:3072
	s_add_u32 s40, s40, 0x40000
	s_addc_u32 s41, s41, 0
	s_mov_b32 m0, s45
	ds_read_b128 v[190:193], v175 offset:32768
	ds_read_b128 v[194:197], v175 offset:33792
	ds_read_b128 v[198:201], v175 offset:34816
	ds_read_b128 v[202:205], v175 offset:35840
	ds_read_b128 v[206:209], v175 offset:36864
	ds_read_b128 v[210:213], v175 offset:37888
	ds_read_b128 v[214:217], v175 offset:38912
	ds_read_b128 v[218:221], v175 offset:39936
	global_load_lds_dwordx4 v144, s[40:41]
	s_mov_b32 m0, s46
	s_nop 0
	global_load_lds_dwordx4 v148, s[40:41]
	s_waitcnt vmcnt(8)
	s_waitcnt lgkmcnt(0)
	s_barrier
	s_setprio 1
	s_waitcnt lgkmcnt(0)
	v_mfma_f32_16x16x32_bf16 v[124:127], v[128:131], v[190:193], v[124:127]
	v_mfma_f32_16x16x32_bf16 v[120:123], v[136:139], v[190:193], v[120:123]
	v_mfma_f32_16x16x32_bf16 v[108:111], v[128:131], v[198:201], v[108:111]
	v_mfma_f32_16x16x32_bf16 v[104:107], v[136:139], v[198:201], v[104:107]
	v_mfma_f32_16x16x32_bf16 v[92:95], v[128:131], v[206:209], v[92:95]
	v_mfma_f32_16x16x32_bf16 v[88:91], v[136:139], v[206:209], v[88:91]
	v_mfma_f32_16x16x32_bf16 v[76:79], v[128:131], v[214:217], v[76:79]
	v_mfma_f32_16x16x32_bf16 v[72:75], v[136:139], v[214:217], v[72:75]
	v_mfma_f32_16x16x32_bf16 v[124:127], v[132:135], v[194:197], v[124:127]
	v_mfma_f32_16x16x32_bf16 v[120:123], v[140:143], v[194:197], v[120:123]
	v_mfma_f32_16x16x32_bf16 v[108:111], v[132:135], v[202:205], v[108:111]
	v_mfma_f32_16x16x32_bf16 v[104:107], v[140:143], v[202:205], v[104:107]
	v_mfma_f32_16x16x32_bf16 v[92:95], v[132:135], v[210:213], v[92:95]
	v_mfma_f32_16x16x32_bf16 v[88:91], v[140:143], v[210:213], v[88:91]
	v_mfma_f32_16x16x32_bf16 v[76:79], v[132:135], v[218:221], v[76:79]
	v_mfma_f32_16x16x32_bf16 v[72:75], v[140:143], v[218:221], v[72:75]
	s_setprio 0
	s_setprio 1
	v_mfma_f32_16x16x32_bf16 v[116:119], v[160:163], v[190:193], v[116:119]
	v_mfma_f32_16x16x32_bf16 v[112:115], v[182:185], v[190:193], v[112:115]
	v_mfma_f32_16x16x32_bf16 v[100:103], v[160:163], v[198:201], v[100:103]
	v_mfma_f32_16x16x32_bf16 v[96:99], v[182:185], v[198:201], v[96:99]
	v_mfma_f32_16x16x32_bf16 v[84:87], v[160:163], v[206:209], v[84:87]
	v_mfma_f32_16x16x32_bf16 v[80:83], v[182:185], v[206:209], v[80:83]
	v_mfma_f32_16x16x32_bf16 v[68:71], v[160:163], v[214:217], v[68:71]
	v_mfma_f32_16x16x32_bf16 v[64:67], v[182:185], v[214:217], v[64:67]
	v_mfma_f32_16x16x32_bf16 v[116:119], v[178:181], v[194:197], v[116:119]
	v_mfma_f32_16x16x32_bf16 v[112:115], v[186:189], v[194:197], v[112:115]
	v_mfma_f32_16x16x32_bf16 v[100:103], v[178:181], v[202:205], v[100:103]
	v_mfma_f32_16x16x32_bf16 v[96:99], v[186:189], v[202:205], v[96:99]
	v_mfma_f32_16x16x32_bf16 v[84:87], v[178:181], v[210:213], v[84:87]
	v_mfma_f32_16x16x32_bf16 v[80:83], v[186:189], v[210:213], v[80:83]
	v_mfma_f32_16x16x32_bf16 v[68:71], v[178:181], v[218:221], v[68:71]
	v_mfma_f32_16x16x32_bf16 v[64:67], v[186:189], v[218:221], v[64:67]
	s_setprio 0
	s_barrier
	s_add_u32 s98, s40, 0xfffc0080
	s_addc_u32 s99, s41, -1
	s_add_u32 s100, s38, 0x80
	s_addc_u32 s101, s39, 0
	s_add_i32 s40, s65, s30
	s_mov_b32 m0, s40
	ds_read_b128 v[190:193], v175 offset:49152
	ds_read_b128 v[194:197], v175 offset:50176
	ds_read_b128 v[198:201], v175 offset:51200
	ds_read_b128 v[202:205], v175 offset:52224
	ds_read_b128 v[206:209], v175 offset:53248
	ds_read_b128 v[210:213], v175 offset:54272
	ds_read_b128 v[214:217], v175 offset:55296
	ds_read_b128 v[218:221], v175 offset:56320
	global_load_lds_dwordx4 v146, s[100:101]
	s_add_i32 m0, s40, 0x2000
	s_add_u32 s38, s38, 0x40080
	s_addc_u32 s39, s39, 0
	s_add_i32 s40, s66, s30
	global_load_lds_dwordx4 v150, s[100:101]
	s_mov_b32 m0, s40
	s_nop 0
	global_load_lds_dwordx4 v146, s[38:39]
	s_add_i32 m0, s40, 0x2000
	s_nop 0
	global_load_lds_dwordx4 v150, s[38:39]
	s_mov_b32 m0, s47
	s_nop 0
	global_load_lds_dwordx4 v144, s[98:99]
	s_mov_b32 m0, s48
	s_nop 0
	global_load_lds_dwordx4 v148, s[98:99]
	s_waitcnt vmcnt(8)
	s_waitcnt lgkmcnt(0)
	s_barrier
	s_setprio 1
	s_waitcnt lgkmcnt(0)
	v_mfma_f32_16x16x32_bf16 v[60:63], v[128:131], v[190:193], v[60:63]
	v_mfma_f32_16x16x32_bf16 v[56:59], v[136:139], v[190:193], v[56:59]
	v_mfma_f32_16x16x32_bf16 v[44:47], v[128:131], v[198:201], v[44:47]
	v_mfma_f32_16x16x32_bf16 v[40:43], v[136:139], v[198:201], v[40:43]
	v_mfma_f32_16x16x32_bf16 v[28:31], v[128:131], v[206:209], v[28:31]
	v_mfma_f32_16x16x32_bf16 v[24:27], v[136:139], v[206:209], v[24:27]
	v_mfma_f32_16x16x32_bf16 v[12:15], v[128:131], v[214:217], v[12:15]
	v_mfma_f32_16x16x32_bf16 v[8:11], v[136:139], v[214:217], v[8:11]
	v_mfma_f32_16x16x32_bf16 v[60:63], v[132:135], v[194:197], v[60:63]
	v_mfma_f32_16x16x32_bf16 v[56:59], v[140:143], v[194:197], v[56:59]
	v_mfma_f32_16x16x32_bf16 v[44:47], v[132:135], v[202:205], v[44:47]
	v_mfma_f32_16x16x32_bf16 v[40:43], v[140:143], v[202:205], v[40:43]
	v_mfma_f32_16x16x32_bf16 v[28:31], v[132:135], v[210:213], v[28:31]
	v_mfma_f32_16x16x32_bf16 v[24:27], v[140:143], v[210:213], v[24:27]
	v_mfma_f32_16x16x32_bf16 v[12:15], v[132:135], v[218:221], v[12:15]
	v_mfma_f32_16x16x32_bf16 v[8:11], v[140:143], v[218:221], v[8:11]
	s_setprio 0
	s_setprio 1
	v_mfma_f32_16x16x32_bf16 v[52:55], v[160:163], v[190:193], v[52:55]
	v_mfma_f32_16x16x32_bf16 v[48:51], v[182:185], v[190:193], v[48:51]
	v_mfma_f32_16x16x32_bf16 v[36:39], v[160:163], v[198:201], v[36:39]
	v_mfma_f32_16x16x32_bf16 v[32:35], v[182:185], v[198:201], v[32:35]
	v_mfma_f32_16x16x32_bf16 v[20:23], v[160:163], v[206:209], v[20:23]
	v_mfma_f32_16x16x32_bf16 v[16:19], v[182:185], v[206:209], v[16:19]
	v_mfma_f32_16x16x32_bf16 v[4:7], v[160:163], v[214:217], v[4:7]
	v_mfma_f32_16x16x32_bf16 v[0:3], v[182:185], v[214:217], v[0:3]
	v_mfma_f32_16x16x32_bf16 v[52:55], v[178:181], v[194:197], v[52:55]
	v_mfma_f32_16x16x32_bf16 v[48:51], v[186:189], v[194:197], v[48:51]
	v_mfma_f32_16x16x32_bf16 v[36:39], v[178:181], v[202:205], v[36:39]
	v_mfma_f32_16x16x32_bf16 v[32:35], v[186:189], v[202:205], v[32:35]
	v_mfma_f32_16x16x32_bf16 v[20:23], v[178:181], v[210:213], v[20:23]
	v_mfma_f32_16x16x32_bf16 v[16:19], v[186:189], v[210:213], v[16:19]
	v_mfma_f32_16x16x32_bf16 v[4:7], v[178:181], v[218:221], v[4:7]
	v_mfma_f32_16x16x32_bf16 v[0:3], v[186:189], v[218:221], v[0:3]
	s_setprio 0
	s_barrier
	s_add_i32 s64, s64, 2
	s_add_u32 s36, s36, 0x100
	s_addc_u32 s37, s37, 0
	s_add_u32 s62, s62, 0x100
	s_addc_u32 s63, s63, 0
	s_cmp_gt_u32 s64, 13
	s_cbranch_scc0 .LBB0_1556
	s_and_b64 vcc, exec, s[12:13]
	s_cbranch_vccz .LBB0_1559
	s_barrier

; #define PG8_STAGE(bufoff, gbase, voff) do { _Pragma("unroll") for (int _i = 0; _i < 2; ++_i) \
;         __builtin_amdgcn_global_load_lds((const unsigned*)((const char*)(gbase) + (voff)[_i]), (PG8_LAS unsigned*)(lds + (bufoff) + ldsw + _i * 8192), 16, 0, 0); } while (0)
; #define PG8_LDA(dst, b, h) do { _Pragma("unroll") for (int m = 0; m < 4; ++m) _Pragma("unroll") for (int k = 0; k < 2; ++k) dst[m][k] = *(const PG8_LAS bf16x8*)(lds + PG8_SA(b, h) + aoff + m * 2048 + k * 1024); } while (0)
; #define PG8_LDB(dst, b, h) do { _Pragma("unroll") for (int n = 0; n < 2; ++n) _Pragma("unroll") for (int k = 0; k < 2; ++k) dst[n][k] = *(const PG8_LAS bf16x8*)(lds + PG8_SB(b, h) + boff + n * 2048 + k * 1024); } while (0)
; #define PG8_MMA(ai, bj, At, Bt) do { __builtin_amdgcn_s_setprio(1); _Pragma("unroll") for (int m = 0; m < 4; ++m) _Pragma("unroll") for (int n = 0; n < 2; ++n) _Pragma("unroll") for (int k = 0; k < 2; ++k) \
;         acc[ai][bj][m][n] = __builtin_amdgcn_mfma_f32_16x16x32_bf16(Bt[n][k], At[m][k], acc[ai][bj][m][n], 0, 0, 0); __builtin_amdgcn_s_setprio(0); } while (0)
; #define PG8_WAIT_V(n) asm volatile("s_waitcnt vmcnt(" #n ")" ::: "memory")
; #define PG8_WAIT_L(n) asm volatile("s_waitcnt lgkmcnt(" #n ")" ::: "memory")
; #define PG8_BAR __builtin_amdgcn_s_barrier()
; #define PG8_SCHED __builtin_amdgcn_sched_barrier(0)
; template <class Epi, class Sched, bool ALIGN_EPI = false, bool SP2 = false>
; __device__ __forceinline__ void gemm_phase(PG8_LAS unsigned char* lds, const Gemm g, const Sched& S, const Epi& E) {
;     ...
;             PG8_LDB(B0, 0, 0); PG8_LDB(B1, 0, 1); PG8_SCHED; PG8_LDA(At, 0, 0); PG8_STAGE(PG8_SA(1, 1), a1 + hstep, voffA);
;             PG8_WAIT_V(8); PG8_WAIT_L(0); PG8_BAR; PG8_MMA(0, 0, At, B0); PG8_MMA(0, 1, At, B1); PG8_BAR; PG8_SCHED;
;             PG8_LDA(At, 0, 1); PG8_STAGE(PG8_SB(0, 0), b2, voffB); PG8_STAGE(PG8_SB(0, 1), b2 + hstep, voffB); PG8_STAGE(PG8_SA(0, 0), a2, voffA);
;             PG8_WAIT_V(8); PG8_WAIT_L(0); PG8_BAR; PG8_MMA(1, 0, At, B0); PG8_MMA(1, 1, At, B1); PG8_BAR; PG8_SCHED;
.LBB0_1641:
	ds_read_b128 v[144:147], v153
	ds_read_b128 v[156:159], v153 offset:1024
	ds_read_b128 v[160:163], v153 offset:2048
	ds_read_b128 v[164:167], v153 offset:3072
	ds_read_b128 v[168:171], v154
	ds_read_b128 v[172:175], v154 offset:1024
	ds_read_b128 v[176:179], v154 offset:2048
	ds_read_b128 v[180:183], v154 offset:3072
	s_add_u32 s30, s28, 0xfff00080
	s_addc_u32 s31, s29, -1
	s_cmp_eq_u32 s58, 60
	s_cselect_b32 s35, s21, s31
	s_cselect_b32 s34, s54, s30
	s_cselect_b32 s31, s19, s57
	s_cselect_b32 s30, s55, s56
	s_add_i32 m0, s39, 0xc000
	ds_read_b128 v[184:187], v155
	ds_read_b128 v[188:191], v155 offset:1024
	ds_read_b128 v[192:195], v155 offset:2048
	ds_read_b128 v[196:199], v155 offset:3072
	ds_read_b128 v[200:203], v155 offset:4096
	ds_read_b128 v[204:207], v155 offset:5120
	ds_read_b128 v[208:211], v155 offset:6144
	ds_read_b128 v[212:215], v155 offset:7168
	global_load_lds_dwordx4 v136, s[28:29]
	s_add_i32 m0, s39, 0xe000
	s_nop 0
	global_load_lds_dwordx4 v138, s[28:29]
	s_waitcnt vmcnt(8)
	s_waitcnt lgkmcnt(0)
	s_barrier
	s_setprio 1
	s_waitcnt lgkmcnt(0)
	v_mfma_f32_16x16x32_bf16 v[124:127], v[144:147], v[184:187], v[124:127]
	v_mfma_f32_16x16x32_bf16 v[120:123], v[160:163], v[184:187], v[120:123]
	v_mfma_f32_16x16x32_bf16 v[108:111], v[144:147], v[192:195], v[108:111]
	v_mfma_f32_16x16x32_bf16 v[104:107], v[160:163], v[192:195], v[104:107]
	v_mfma_f32_16x16x32_bf16 v[92:95], v[144:147], v[200:203], v[92:95]
	v_mfma_f32_16x16x32_bf16 v[88:91], v[160:163], v[200:203], v[88:91]
	v_mfma_f32_16x16x32_bf16 v[76:79], v[144:147], v[208:211], v[76:79]
	v_mfma_f32_16x16x32_bf16 v[72:75], v[160:163], v[208:211], v[72:75]
	v_mfma_f32_16x16x32_bf16 v[124:127], v[156:159], v[188:191], v[124:127]
	v_mfma_f32_16x16x32_bf16 v[120:123], v[164:167], v[188:191], v[120:123]
	v_mfma_f32_16x16x32_bf16 v[108:111], v[156:159], v[196:199], v[108:111]
	v_mfma_f32_16x16x32_bf16 v[104:107], v[164:167], v[196:199], v[104:107]
	v_mfma_f32_16x16x32_bf16 v[92:95], v[156:159], v[204:207], v[92:95]
	v_mfma_f32_16x16x32_bf16 v[88:91], v[164:167], v[204:207], v[88:91]
	v_mfma_f32_16x16x32_bf16 v[76:79], v[156:159], v[212:215], v[76:79]
	v_mfma_f32_16x16x32_bf16 v[72:75], v[164:167], v[212:215], v[72:75]
	s_setprio 0
	s_setprio 1
	v_mfma_f32_16x16x32_bf16 v[116:119], v[168:171], v[184:187], v[116:119]
	v_mfma_f32_16x16x32_bf16 v[112:115], v[176:179], v[184:187], v[112:115]
	v_mfma_f32_16x16x32_bf16 v[100:103], v[168:171], v[192:195], v[100:103]
	v_mfma_f32_16x16x32_bf16 v[96:99], v[176:179], v[192:195], v[96:99]
	v_mfma_f32_16x16x32_bf16 v[84:87], v[168:171], v[200:203], v[84:87]
	v_mfma_f32_16x16x32_bf16 v[80:83], v[176:179], v[200:203], v[80:83]
	v_mfma_f32_16x16x32_bf16 v[68:71], v[168:171], v[208:211], v[68:71]
	v_mfma_f32_16x16x32_bf16 v[64:67], v[176:179], v[208:211], v[64:67]
	v_mfma_f32_16x16x32_bf16 v[116:119], v[172:175], v[188:191], v[116:119]
	v_mfma_f32_16x16x32_bf16 v[112:115], v[180:183], v[188:191], v[112:115]
	v_mfma_f32_16x16x32_bf16 v[100:103], v[172:175], v[196:199], v[100:103]
	v_mfma_f32_16x16x32_bf16 v[96:99], v[180:183], v[196:199], v[96:99]
	v_mfma_f32_16x16x32_bf16 v[84:87], v[172:175], v[204:207], v[84:87]
	v_mfma_f32_16x16x32_bf16 v[80:83], v[180:183], v[204:207], v[80:83]
	v_mfma_f32_16x16x32_bf16 v[68:71], v[172:175], v[212:215], v[68:71]
	v_mfma_f32_16x16x32_bf16 v[64:67], v[180:183], v[212:215], v[64:67]
	s_setprio 0
	s_barrier
	s_add_i32 s59, s48, s38
	s_mov_b32 m0, s59
	ds_read_b128 v[184:187], v155 offset:16384
	ds_read_b128 v[188:191], v155 offset:17408
	ds_read_b128 v[192:195], v155 offset:18432
	ds_read_b128 v[196:199], v155 offset:19456
	ds_read_b128 v[200:203], v155 offset:20480
	ds_read_b128 v[204:207], v155 offset:21504
	ds_read_b128 v[208:211], v155 offset:22528
	ds_read_b128 v[212:215], v155 offset:23552
	global_load_lds_dwordx4 v130, s[30:31]
	s_add_i32 m0, s59, 0x2000
	s_add_u32 s60, s30, 0x100000
	s_addc_u32 s61, s31, 0
	s_add_i32 s59, s49, s38
	global_load_lds_dwordx4 v134, s[30:31]
	s_mov_b32 m0, s59
	s_nop 0
	global_load_lds_dwordx4 v130, s[60:61]
	s_add_i32 m0, s59, 0x2000
	s_nop 0
	global_load_lds_dwordx4 v134, s[60:61]
	s_mov_b32 m0, s39
	s_nop 0
	global_load_lds_dwordx4 v128, s[34:35]
	s_mov_b32 m0, s40
	s_nop 0
	global_load_lds_dwordx4 v132, s[34:35]
	s_waitcnt vmcnt(8)
	s_waitcnt lgkmcnt(0)
	s_barrier
	s_setprio 1
	s_waitcnt lgkmcnt(0)
	v_mfma_f32_16x16x32_bf16 v[60:63], v[144:147], v[184:187], v[60:63]
	v_mfma_f32_16x16x32_bf16 v[56:59], v[160:163], v[184:187], v[56:59]
	v_mfma_f32_16x16x32_bf16 v[44:47], v[144:147], v[192:195], v[44:47]
	v_mfma_f32_16x16x32_bf16 v[40:43], v[160:163], v[192:195], v[40:43]
	v_mfma_f32_16x16x32_bf16 v[28:31], v[144:147], v[200:203], v[28:31]
	v_mfma_f32_16x16x32_bf16 v[24:27], v[160:163], v[200:203], v[24:27]
	v_mfma_f32_16x16x32_bf16 v[12:15], v[144:147], v[208:211], v[12:15]
	v_mfma_f32_16x16x32_bf16 v[8:11], v[160:163], v[208:211], v[8:11]
	v_mfma_f32_16x16x32_bf16 v[60:63], v[156:159], v[188:191], v[60:63]
	v_mfma_f32_16x16x32_bf16 v[56:59], v[164:167], v[188:191], v[56:59]
	v_mfma_f32_16x16x32_bf16 v[44:47], v[156:159], v[196:199], v[44:47]
	v_mfma_f32_16x16x32_bf16 v[40:43], v[164:167], v[196:199], v[40:43]
	v_mfma_f32_16x16x32_bf16 v[28:31], v[156:159], v[204:207], v[28:31]
	v_mfma_f32_16x16x32_bf16 v[24:27], v[164:167], v[204:207], v[24:27]
	v_mfma_f32_16x16x32_bf16 v[12:15], v[156:159], v[212:215], v[12:15]
	v_mfma_f32_16x16x32_bf16 v[8:11], v[164:167], v[212:215], v[8:11]
	s_setprio 0
	s_setprio 1
	v_mfma_f32_16x16x32_bf16 v[52:55], v[168:171], v[184:187], v[52:55]
	v_mfma_f32_16x16x32_bf16 v[48:51], v[176:179], v[184:187], v[48:51]
	v_mfma_f32_16x16x32_bf16 v[36:39], v[168:171], v[192:195], v[36:39]
	v_mfma_f32_16x16x32_bf16 v[32:35], v[176:179], v[192:195], v[32:35]
	v_mfma_f32_16x16x32_bf16 v[20:23], v[168:171], v[200:203], v[20:23]
	v_mfma_f32_16x16x32_bf16 v[16:19], v[176:179], v[200:203], v[16:19]
	v_mfma_f32_16x16x32_bf16 v[4:7], v[168:171], v[208:211], v[4:7]
	v_mfma_f32_16x16x32_bf16 v[0:3], v[176:179], v[208:211], v[0:3]
	v_mfma_f32_16x16x32_bf16 v[52:55], v[172:175], v[188:191], v[52:55]
	v_mfma_f32_16x16x32_bf16 v[48:51], v[180:183], v[188:191], v[48:51]
	v_mfma_f32_16x16x32_bf16 v[36:39], v[172:175], v[196:199], v[36:39]
	v_mfma_f32_16x16x32_bf16 v[32:35], v[180:183], v[196:199], v[32:35]
	v_mfma_f32_16x16x32_bf16 v[20:23], v[172:175], v[204:207], v[20:23]
	v_mfma_f32_16x16x32_bf16 v[16:19], v[180:183], v[204:207], v[16:19]
	v_mfma_f32_16x16x32_bf16 v[4:7], v[172:175], v[212:215], v[4:7]
	v_mfma_f32_16x16x32_bf16 v[0:3], v[180:183], v[212:215], v[0:3]
	s_setprio 0
	s_barrier
; #define PG8_STAGE(bufoff, gbase, voff) do { _Pragma("unroll") for (int _i = 0; _i < 2; ++_i) \
;         __builtin_amdgcn_global_load_lds((const unsigned*)((const char*)(gbase) + (voff)[_i]), (PG8_LAS unsigned*)(lds + (bufoff) + ldsw + _i * 8192), 16, 0, 0); } while (0)
; #define PG8_LDA(dst, b, h) do { _Pragma("unroll") for (int m = 0; m < 4; ++m) _Pragma("unroll") for (int k = 0; k < 2; ++k) dst[m][k] = *(const PG8_LAS bf16x8*)(lds + PG8_SA(b, h) + aoff + m * 2048 + k * 1024); } while (0)
; #define PG8_LDB(dst, b, h) do { _Pragma("unroll") for (int n = 0; n < 2; ++n) _Pragma("unroll") for (int k = 0; k < 2; ++k) dst[n][k] = *(const PG8_LAS bf16x8*)(lds + PG8_SB(b, h) + boff + n * 2048 + k * 1024); } while (0)
; #define PG8_MMA(ai, bj, At, Bt) do { __builtin_amdgcn_s_setprio(1); _Pragma("unroll") for (int m = 0; m < 4; ++m) _Pragma("unroll") for (int n = 0; n < 2; ++n) _Pragma("unroll") for (int k = 0; k < 2; ++k) \
;         acc[ai][bj][m][n] = __builtin_amdgcn_mfma_f32_16x16x32_bf16(Bt[n][k], At[m][k], acc[ai][bj][m][n], 0, 0, 0); __builtin_amdgcn_s_setprio(0); } while (0)
; #define PG8_WAIT_V(n) asm volatile("s_waitcnt vmcnt(" #n ")" ::: "memory")
; #define PG8_WAIT_L(n) asm volatile("s_waitcnt lgkmcnt(" #n ")" ::: "memory")
; #define PG8_BAR __builtin_amdgcn_s_barrier()
; #define PG8_SCHED __builtin_amdgcn_sched_barrier(0)
; template <class Epi, class Sched, bool ALIGN_EPI = false, bool SP2 = false>
; __device__ __forceinline__ void gemm_phase(PG8_LAS unsigned char* lds, const Gemm g, const Sched& S, const Epi& E) {
;     ...
;             PG8_LDB(B0, 1, 0); PG8_LDB(B1, 1, 1); PG8_SCHED; PG8_LDA(At, 1, 0); PG8_STAGE(PG8_SA(0, 1), a2 + hstep, voffA);
;             PG8_WAIT_V(8); PG8_WAIT_L(0); PG8_BAR; PG8_MMA(0, 0, At, B0); PG8_MMA(0, 1, At, B1); PG8_BAR; PG8_SCHED;
	s_add_i32 s59, 0, 0x18000
	s_add_i32 s60, 0, 0x1c000
	v_add_u32_e32 v164, s59, v151
	v_add_u32_e32 v180, s60, v151
	ds_read_b128 v[144:147], v164
	ds_read_b128 v[156:159], v164 offset:1024
	ds_read_b128 v[160:163], v164 offset:2048
	ds_read_b128 v[164:167], v164 offset:3072
	ds_read_b128 v[168:171], v180
	ds_read_b128 v[172:175], v180 offset:1024
	ds_read_b128 v[176:179], v180 offset:2048
	ds_read_b128 v[180:183], v180 offset:3072
	s_add_u32 s34, s34, 0x100000
	s_addc_u32 s35, s35, 0
	s_mov_b32 m0, s41
	ds_read_b128 v[184:187], v155 offset:32768
	ds_read_b128 v[188:191], v155 offset:33792
	ds_read_b128 v[192:195], v155 offset:34816
	ds_read_b128 v[196:199], v155 offset:35840
	ds_read_b128 v[200:203], v155 offset:36864
	ds_read_b128 v[204:207], v155 offset:37888
	ds_read_b128 v[208:211], v155 offset:38912
	ds_read_b128 v[212:215], v155 offset:39936
	global_load_lds_dwordx4 v128, s[34:35]
	s_mov_b32 m0, s42
	s_nop 0
	global_load_lds_dwordx4 v132, s[34:35]
	s_waitcnt vmcnt(8)
	s_waitcnt lgkmcnt(0)
	s_barrier
	s_setprio 1
	s_waitcnt lgkmcnt(0)
	v_mfma_f32_16x16x32_bf16 v[124:127], v[144:147], v[184:187], v[124:127]
	v_mfma_f32_16x16x32_bf16 v[120:123], v[160:163], v[184:187], v[120:123]
	v_mfma_f32_16x16x32_bf16 v[108:111], v[144:147], v[192:195], v[108:111]
	v_mfma_f32_16x16x32_bf16 v[104:107], v[160:163], v[192:195], v[104:107]
	v_mfma_f32_16x16x32_bf16 v[92:95], v[144:147], v[200:203], v[92:95]
	v_mfma_f32_16x16x32_bf16 v[88:91], v[160:163], v[200:203], v[88:91]
	v_mfma_f32_16x16x32_bf16 v[76:79], v[144:147], v[208:211], v[76:79]
	v_mfma_f32_16x16x32_bf16 v[72:75], v[160:163], v[208:211], v[72:75]
	v_mfma_f32_16x16x32_bf16 v[124:127], v[156:159], v[188:191], v[124:127]
	v_mfma_f32_16x16x32_bf16 v[120:123], v[164:167], v[188:191], v[120:123]
	v_mfma_f32_16x16x32_bf16 v[108:111], v[156:159], v[196:199], v[108:111]
	v_mfma_f32_16x16x32_bf16 v[104:107], v[164:167], v[196:199], v[104:107]
	v_mfma_f32_16x16x32_bf16 v[92:95], v[156:159], v[204:207], v[92:95]
	v_mfma_f32_16x16x32_bf16 v[88:91], v[164:167], v[204:207], v[88:91]
	v_mfma_f32_16x16x32_bf16 v[76:79], v[156:159], v[212:215], v[76:79]
	v_mfma_f32_16x16x32_bf16 v[72:75], v[164:167], v[212:215], v[72:75]
	s_setprio 0
	s_setprio 1
	v_mfma_f32_16x16x32_bf16 v[116:119], v[168:171], v[184:187], v[116:119]
	v_mfma_f32_16x16x32_bf16 v[112:115], v[176:179], v[184:187], v[112:115]
	v_mfma_f32_16x16x32_bf16 v[100:103], v[168:171], v[192:195], v[100:103]
	v_mfma_f32_16x16x32_bf16 v[96:99], v[176:179], v[192:195], v[96:99]
	v_mfma_f32_16x16x32_bf16 v[84:87], v[168:171], v[200:203], v[84:87]
	v_mfma_f32_16x16x32_bf16 v[80:83], v[176:179], v[200:203], v[80:83]
	v_mfma_f32_16x16x32_bf16 v[68:71], v[168:171], v[208:211], v[68:71]
	v_mfma_f32_16x16x32_bf16 v[64:67], v[176:179], v[208:211], v[64:67]
	v_mfma_f32_16x16x32_bf16 v[116:119], v[172:175], v[188:191], v[116:119]
	v_mfma_f32_16x16x32_bf16 v[112:115], v[180:183], v[188:191], v[112:115]
	v_mfma_f32_16x16x32_bf16 v[100:103], v[172:175], v[196:199], v[100:103]
	v_mfma_f32_16x16x32_bf16 v[96:99], v[180:183], v[196:199], v[96:99]
	v_mfma_f32_16x16x32_bf16 v[84:87], v[172:175], v[204:207], v[84:87]
	v_mfma_f32_16x16x32_bf16 v[80:83], v[180:183], v[204:207], v[80:83]
	v_mfma_f32_16x16x32_bf16 v[68:71], v[172:175], v[212:215], v[68:71]
	v_mfma_f32_16x16x32_bf16 v[64:67], v[180:183], v[212:215], v[64:67]
	s_setprio 0
	s_barrier
; #define PG8_STAGE(bufoff, gbase, voff) do { _Pragma("unroll") for (int _i = 0; _i < 2; ++_i) \
;         __builtin_amdgcn_global_load_lds((const unsigned*)((const char*)(gbase) + (voff)[_i]), (PG8_LAS unsigned*)(lds + (bufoff) + ldsw + _i * 8192), 16, 0, 0); } while (0)
; #define PG8_LDA(dst, b, h) do { _Pragma("unroll") for (int m = 0; m < 4; ++m) _Pragma("unroll") for (int k = 0; k < 2; ++k) dst[m][k] = *(const PG8_LAS bf16x8*)(lds + PG8_SA(b, h) + aoff + m * 2048 + k * 1024); } while (0)
; #define PG8_MMA(ai, bj, At, Bt) do { __builtin_amdgcn_s_setprio(1); _Pragma("unroll") for (int m = 0; m < 4; ++m) _Pragma("unroll") for (int n = 0; n < 2; ++n) _Pragma("unroll") for (int k = 0; k < 2; ++k) \
;         acc[ai][bj][m][n] = __builtin_amdgcn_mfma_f32_16x16x32_bf16(Bt[n][k], At[m][k], acc[ai][bj][m][n], 0, 0, 0); __builtin_amdgcn_s_setprio(0); } while (0)
; #define PG8_WAIT_V(n) asm volatile("s_waitcnt vmcnt(" #n ")" ::: "memory")
; #define PG8_WAIT_L(n) asm volatile("s_waitcnt lgkmcnt(" #n ")" ::: "memory")
; #define PG8_BAR __builtin_amdgcn_s_barrier()
; #define PG8_SCHED __builtin_amdgcn_sched_barrier(0)
; template <class Epi, class Sched, bool ALIGN_EPI = false, bool SP2 = false>
; __device__ __forceinline__ void gemm_phase(PG8_LAS unsigned char* lds, const Gemm g, const Sched& S, const Epi& E) {
;     ...
;         for (int t = 0; t < nt; t += 2) {
;             const bool last = (t == nt - 2);
;     ...
;             PG8_LDA(At, 1, 1); PG8_STAGE(PG8_SB(1, 0), b3, voffB); PG8_STAGE(PG8_SB(1, 1), b3 + hstep, voffB); PG8_STAGE(PG8_SA(1, 0), a3, voffA);
;             PG8_WAIT_V(8); PG8_WAIT_L(0); PG8_BAR; PG8_MMA(1, 0, At, B0); PG8_MMA(1, 1, At, B1); PG8_BAR; PG8_SCHED;
	s_add_u32 s98, s34, 0xfff00080
	s_addc_u32 s99, s35, -1
	s_add_u32 s100, s30, 0x80
	s_addc_u32 s101, s31, 0
	s_add_i32 s34, s59, s38
	s_mov_b32 m0, s34
	ds_read_b128 v[184:187], v155 offset:49152
	ds_read_b128 v[188:191], v155 offset:50176
	ds_read_b128 v[192:195], v155 offset:51200
	ds_read_b128 v[196:199], v155 offset:52224
	ds_read_b128 v[200:203], v155 offset:53248
	ds_read_b128 v[204:207], v155 offset:54272
	ds_read_b128 v[208:211], v155 offset:55296
	ds_read_b128 v[212:215], v155 offset:56320
	global_load_lds_dwordx4 v130, s[100:101]
	s_add_i32 m0, s34, 0x2000
	s_add_u32 s30, s30, 0x100080
	s_addc_u32 s31, s31, 0
	s_add_i32 s34, s60, s38
	global_load_lds_dwordx4 v134, s[100:101]
	s_mov_b32 m0, s34
	s_nop 0
	global_load_lds_dwordx4 v130, s[30:31]
	s_add_i32 m0, s34, 0x2000
	s_nop 0
	global_load_lds_dwordx4 v134, s[30:31]
	s_mov_b32 m0, s44
	s_nop 0
	global_load_lds_dwordx4 v128, s[98:99]
	s_mov_b32 m0, s45
	s_nop 0
	global_load_lds_dwordx4 v132, s[98:99]
	s_waitcnt vmcnt(8)
	s_waitcnt lgkmcnt(0)
	s_barrier
	s_setprio 1
	s_waitcnt lgkmcnt(0)
	v_mfma_f32_16x16x32_bf16 v[60:63], v[144:147], v[184:187], v[60:63]
	v_mfma_f32_16x16x32_bf16 v[56:59], v[160:163], v[184:187], v[56:59]
	v_mfma_f32_16x16x32_bf16 v[44:47], v[144:147], v[192:195], v[44:47]
	v_mfma_f32_16x16x32_bf16 v[40:43], v[160:163], v[192:195], v[40:43]
	v_mfma_f32_16x16x32_bf16 v[28:31], v[144:147], v[200:203], v[28:31]
	v_mfma_f32_16x16x32_bf16 v[24:27], v[160:163], v[200:203], v[24:27]
	v_mfma_f32_16x16x32_bf16 v[12:15], v[144:147], v[208:211], v[12:15]
	v_mfma_f32_16x16x32_bf16 v[8:11], v[160:163], v[208:211], v[8:11]
	v_mfma_f32_16x16x32_bf16 v[60:63], v[156:159], v[188:191], v[60:63]
	v_mfma_f32_16x16x32_bf16 v[56:59], v[164:167], v[188:191], v[56:59]
	v_mfma_f32_16x16x32_bf16 v[44:47], v[156:159], v[196:199], v[44:47]
	v_mfma_f32_16x16x32_bf16 v[40:43], v[164:167], v[196:199], v[40:43]
	v_mfma_f32_16x16x32_bf16 v[28:31], v[156:159], v[204:207], v[28:31]
	v_mfma_f32_16x16x32_bf16 v[24:27], v[164:167], v[204:207], v[24:27]
	v_mfma_f32_16x16x32_bf16 v[12:15], v[156:159], v[212:215], v[12:15]
	v_mfma_f32_16x16x32_bf16 v[8:11], v[164:167], v[212:215], v[8:11]
	s_setprio 0
	s_setprio 1
	v_mfma_f32_16x16x32_bf16 v[52:55], v[168:171], v[184:187], v[52:55]
	v_mfma_f32_16x16x32_bf16 v[48:51], v[176:179], v[184:187], v[48:51]
	v_mfma_f32_16x16x32_bf16 v[36:39], v[168:171], v[192:195], v[36:39]
	v_mfma_f32_16x16x32_bf16 v[32:35], v[176:179], v[192:195], v[32:35]
	v_mfma_f32_16x16x32_bf16 v[20:23], v[168:171], v[200:203], v[20:23]
	v_mfma_f32_16x16x32_bf16 v[16:19], v[176:179], v[200:203], v[16:19]
	v_mfma_f32_16x16x32_bf16 v[4:7], v[168:171], v[208:211], v[4:7]
	v_mfma_f32_16x16x32_bf16 v[0:3], v[176:179], v[208:211], v[0:3]
	v_mfma_f32_16x16x32_bf16 v[52:55], v[172:175], v[188:191], v[52:55]
	v_mfma_f32_16x16x32_bf16 v[48:51], v[180:183], v[188:191], v[48:51]
	v_mfma_f32_16x16x32_bf16 v[36:39], v[172:175], v[196:199], v[36:39]
	v_mfma_f32_16x16x32_bf16 v[32:35], v[180:183], v[196:199], v[32:35]
	v_mfma_f32_16x16x32_bf16 v[20:23], v[172:175], v[204:207], v[20:23]
	v_mfma_f32_16x16x32_bf16 v[16:19], v[180:183], v[204:207], v[16:19]
	v_mfma_f32_16x16x32_bf16 v[4:7], v[172:175], v[212:215], v[4:7]
	v_mfma_f32_16x16x32_bf16 v[0:3], v[180:183], v[212:215], v[0:3]
	s_setprio 0
	s_barrier
	s_add_i32 s58, s58, 2
	s_add_u32 s28, s28, 0x100
	s_addc_u32 s29, s29, 0
	s_add_u32 s56, s56, 0x100
	s_addc_u32 s57, s57, 0
	s_cmp_gt_u32 s58, 61
	s_cbranch_scc0 .LBB0_1641
	v_mbcnt_lo_u32_b32 v234, -1, 0
	v_mbcnt_hi_u32_b32 v234, -1, v234
	v_bfe_u32 v234, v234, 3, 1
	v_sub_u32_e32 v231, 0, v234
	v_and_b32_e32 v230, 0xffff8010, v231
	v_and_b32_e32 v235, 0x7ff0, v231
	v_sub_u32_e32 v244, 0x8000, v235
	v_mov_b32_e32 v245, 0
	s_mov_b32 s98, 0xff00ff
	s_mov_b32 s99, 0xff00ff
	s_and_b64 vcc, exec, s[8:9]
	s_cbranch_vccz .LBB0_1644
	s_barrier
